# code placement: every 32-MFMA cluster in the GEMM K-loops starts 8-byte aligned (s_nop 0 pads in front of clusters at 4 mod 8, compensated per loop)
# baseline (speedup 1.0000x reference)
.LBB0_111:
	s_cmp_lg_u32 s7, 0
	v_mov_b32_e32 v133, v137
	v_mov_b32_e32 v135, v137
	v_mov_b32_e32 v131, v137
	s_cbranch_scc0 .LBB0_125
	ds_read_b128 v[2:5], v148
	ds_read_b128 v[6:9], v148 offset:1024
	ds_read_b128 v[10:13], v148 offset:2048
	ds_read_b128 v[14:17], v148 offset:3072
	ds_read_b128 v[18:21], v149
	ds_read_b128 v[22:25], v149 offset:1024
	ds_read_b128 v[26:29], v149 offset:2048
	ds_read_b128 v[30:33], v149 offset:3072
	ds_read_b128 v[34:37], v150
	ds_read_b128 v[38:41], v150 offset:1024
	ds_read_b128 v[42:45], v150 offset:2048
	ds_read_b128 v[46:49], v150 offset:3072
	ds_read_b128 v[50:53], v150 offset:4096
	ds_read_b128 v[54:57], v150 offset:5120
	ds_read_b128 v[58:61], v150 offset:6144
	ds_read_b128 v[62:65], v150 offset:7168
	s_waitcnt vmcnt(24)
	s_waitcnt lgkmcnt(0)
	s_barrier
	s_setprio 1
	s_waitcnt lgkmcnt(0)
	s_nop 0
	v_mfma_f32_16x16x32_bf16 v[66:69], v[2:5], v[34:37], 0
	v_mfma_f32_16x16x32_bf16 v[70:73], v[10:13], v[34:37], 0
	v_mfma_f32_16x16x32_bf16 v[74:77], v[2:5], v[42:45], 0
	v_mfma_f32_16x16x32_bf16 v[78:81], v[10:13], v[42:45], 0
	v_mfma_f32_16x16x32_bf16 v[82:85], v[2:5], v[50:53], 0
	v_mfma_f32_16x16x32_bf16 v[86:89], v[10:13], v[50:53], 0
	v_mfma_f32_16x16x32_bf16 v[90:93], v[2:5], v[58:61], 0
	v_mfma_f32_16x16x32_bf16 v[94:97], v[10:13], v[58:61], 0
	v_mfma_f32_16x16x32_bf16 v[66:69], v[6:9], v[38:41], v[66:69]
	v_mfma_f32_16x16x32_bf16 v[70:73], v[14:17], v[38:41], v[70:73]
	v_mfma_f32_16x16x32_bf16 v[74:77], v[6:9], v[46:49], v[74:77]
	v_mfma_f32_16x16x32_bf16 v[78:81], v[14:17], v[46:49], v[78:81]
	v_mfma_f32_16x16x32_bf16 v[82:85], v[6:9], v[54:57], v[82:85]
	v_mfma_f32_16x16x32_bf16 v[86:89], v[14:17], v[54:57], v[86:89]
	v_mfma_f32_16x16x32_bf16 v[90:93], v[6:9], v[62:65], v[90:93]
	v_mfma_f32_16x16x32_bf16 v[98:101], v[14:17], v[62:65], v[94:97]
	s_setprio 0
	s_setprio 1
	v_mfma_f32_16x16x32_bf16 v[94:97], v[18:21], v[34:37], 0
	v_mfma_f32_16x16x32_bf16 v[34:37], v[26:29], v[34:37], 0
	v_mfma_f32_16x16x32_bf16 v[110:113], v[22:25], v[38:41], v[94:97]
	v_mfma_f32_16x16x32_bf16 v[34:37], v[30:33], v[38:41], v[34:37]
	v_mfma_f32_16x16x32_bf16 v[38:41], v[18:21], v[42:45], 0
	v_mfma_f32_16x16x32_bf16 v[42:45], v[26:29], v[42:45], 0
	v_mfma_f32_16x16x32_bf16 v[38:41], v[22:25], v[46:49], v[38:41]
	v_mfma_f32_16x16x32_bf16 v[46:49], v[30:33], v[46:49], v[42:45]
	v_mfma_f32_16x16x32_bf16 v[42:45], v[18:21], v[50:53], 0
	v_mfma_f32_16x16x32_bf16 v[118:121], v[22:25], v[54:57], v[42:45]
	v_mfma_f32_16x16x32_bf16 v[42:45], v[26:29], v[50:53], 0
	v_mfma_f32_16x16x32_bf16 v[240:243], v[30:33], v[54:57], v[42:45]
	v_mfma_f32_16x16x32_bf16 v[42:45], v[18:21], v[58:61], 0
	v_mfma_f32_16x16x32_bf16 v[122:125], v[22:25], v[62:65], v[42:45]
	v_mfma_f32_16x16x32_bf16 v[42:45], v[26:29], v[58:61], 0
	v_mfma_f32_16x16x32_bf16 v[58:61], v[30:33], v[62:65], v[42:45]
	s_setprio 0
	s_barrier
	v_lshl_add_u64 v[252:253], s[0:1], 0, v[132:133]
	s_add_i32 s7, s75, s59
	v_lshl_add_u64 v[142:143], v[252:253], 0, s[22:23]
	s_mov_b32 m0, s7
	s_nop 0
	ds_read_b128 v[42:45], v150 offset:16384
	ds_read_b128 v[50:53], v150 offset:17408
	ds_read_b128 v[62:65], v150 offset:18432
	ds_read_b128 v[94:97], v150 offset:19456
	ds_read_b128 v[102:105], v150 offset:20480
	ds_read_b128 v[106:109], v150 offset:21504
	ds_read_b128 v[114:117], v150 offset:22528
	ds_read_b128 v[126:129], v150 offset:23552
	global_load_lds_dwordx4 v[142:143], off
	s_add_i32 m0, s7, 0x2000
	v_lshl_add_u64 v[138:139], s[0:1], 0, v[136:137]
	s_add_u32 s44, s0, 0x10100
	v_lshl_add_u64 v[142:143], v[138:139], 0, s[22:23]
	s_addc_u32 s45, s1, 0
	s_add_i32 s7, s76, s59
	global_load_lds_dwordx4 v[142:143], off
	s_mov_b32 m0, s7
	v_lshl_add_u64 v[140:141], s[4:5], 0, v[130:131]
	global_load_lds_dwordx4 v132, s[44:45]
	s_add_i32 m0, s7, 0x2000
	v_lshl_add_u64 v[142:143], v[140:141], 0, s[22:23]
	global_load_lds_dwordx4 v136, s[44:45]
	s_mov_b32 m0, s60
	v_lshl_add_u64 v[54:55], s[4:5], 0, v[134:135]
	global_load_lds_dwordx4 v[142:143], off
	v_lshl_add_u64 v[56:57], v[54:55], 0, s[22:23]
	s_mov_b32 m0, s61
	s_nop 0
	global_load_lds_dwordx4 v[56:57], off
	s_waitcnt vmcnt(24)
	s_waitcnt lgkmcnt(0)
	s_barrier
	s_setprio 1
	s_waitcnt lgkmcnt(0)
	v_mfma_f32_16x16x32_bf16 v[142:145], v[2:5], v[42:45], 0
	v_mfma_f32_16x16x32_bf16 v[156:159], v[2:5], v[62:65], 0
	v_mfma_f32_16x16x32_bf16 v[164:167], v[2:5], v[102:105], 0
	v_mfma_f32_16x16x32_bf16 v[2:5], v[2:5], v[114:117], 0
	v_mfma_f32_16x16x32_bf16 v[172:175], v[6:9], v[126:129], v[2:5]
	v_mfma_f32_16x16x32_bf16 v[2:5], v[10:13], v[114:117], 0
	v_mfma_f32_16x16x32_bf16 v[152:155], v[10:13], v[42:45], 0
	v_mfma_f32_16x16x32_bf16 v[160:163], v[10:13], v[62:65], 0
	v_mfma_f32_16x16x32_bf16 v[168:171], v[10:13], v[102:105], 0
	v_mfma_f32_16x16x32_bf16 v[10:13], v[14:17], v[126:129], v[2:5]
	v_mfma_f32_16x16x32_bf16 v[142:145], v[6:9], v[50:53], v[142:145]
	v_mfma_f32_16x16x32_bf16 v[152:155], v[14:17], v[50:53], v[152:155]
	v_mfma_f32_16x16x32_bf16 v[156:159], v[6:9], v[94:97], v[156:159]
	v_mfma_f32_16x16x32_bf16 v[160:163], v[14:17], v[94:97], v[160:163]
	v_mfma_f32_16x16x32_bf16 v[164:167], v[6:9], v[106:109], v[164:167]
	v_mfma_f32_16x16x32_bf16 v[168:171], v[14:17], v[106:109], v[168:171]
	s_setprio 0
	s_setprio 1
	v_mfma_f32_16x16x32_bf16 v[2:5], v[18:21], v[42:45], 0
	v_mfma_f32_16x16x32_bf16 v[176:179], v[22:25], v[50:53], v[2:5]
	v_mfma_f32_16x16x32_bf16 v[2:5], v[26:29], v[42:45], 0
	v_mfma_f32_16x16x32_bf16 v[180:183], v[30:33], v[50:53], v[2:5]
	v_mfma_f32_16x16x32_bf16 v[2:5], v[18:21], v[62:65], 0
	v_mfma_f32_16x16x32_bf16 v[184:187], v[22:25], v[94:97], v[2:5]
	v_mfma_f32_16x16x32_bf16 v[2:5], v[26:29], v[62:65], 0
	v_mfma_f32_16x16x32_bf16 v[188:191], v[30:33], v[94:97], v[2:5]
	v_mfma_f32_16x16x32_bf16 v[2:5], v[18:21], v[102:105], 0
	v_mfma_f32_16x16x32_bf16 v[192:195], v[22:25], v[106:109], v[2:5]
	v_mfma_f32_16x16x32_bf16 v[2:5], v[26:29], v[102:105], 0
	v_mfma_f32_16x16x32_bf16 v[196:199], v[30:33], v[106:109], v[2:5]
	v_mfma_f32_16x16x32_bf16 v[2:5], v[18:21], v[114:117], 0
	v_mfma_f32_16x16x32_bf16 v[22:25], v[22:25], v[126:129], v[2:5]
	v_mfma_f32_16x16x32_bf16 v[2:5], v[26:29], v[114:117], 0
	v_mfma_f32_16x16x32_bf16 v[200:203], v[30:33], v[126:129], v[2:5]
	s_setprio 0
	s_barrier
	s_add_i32 s7, 0, 0x18000
	s_nop 3
	v_add_u32_e32 v2, s7, v147
	s_add_i32 s14, 0, 0x1c000
	ds_read_b128 v[26:29], v2
	ds_read_b128 v[62:65], v2 offset:1024
	ds_read_b128 v[204:207], v2 offset:2048
	ds_read_b128 v[208:211], v2 offset:3072
	v_add_u32_e32 v2, s14, v147
	ds_read_b128 v[212:215], v2
	ds_read_b128 v[216:219], v2 offset:1024
	ds_read_b128 v[220:223], v2 offset:2048
	ds_read_b128 v[224:227], v2 offset:3072
	s_add_u32 s44, s4, 0x40100
	s_addc_u32 s45, s5, 0
	s_mov_b32 m0, s62
	ds_read_b128 v[2:5], v150 offset:32768
	ds_read_b128 v[6:9], v150 offset:33792
	ds_read_b128 v[14:17], v150 offset:34816
	ds_read_b128 v[18:21], v150 offset:35840
	ds_read_b128 v[126:129], v150 offset:36864
	ds_read_b128 v[228:231], v150 offset:37888
	ds_read_b128 v[232:235], v150 offset:38912
	ds_read_b128 v[236:239], v150 offset:39936
	global_load_lds_dwordx4 v130, s[44:45]
	s_mov_b32 m0, s63
	s_nop 0
	global_load_lds_dwordx4 v134, s[44:45]
	s_waitcnt vmcnt(24)
	s_waitcnt lgkmcnt(0)
	s_barrier
	s_setprio 1
	s_waitcnt lgkmcnt(0)
	v_mfma_f32_16x16x32_bf16 v[30:33], v[26:29], v[2:5], v[66:69]
	v_mfma_f32_16x16x32_bf16 v[114:117], v[62:65], v[6:9], v[30:33]
	v_mfma_f32_16x16x32_bf16 v[30:33], v[204:207], v[2:5], v[70:73]
	v_mfma_f32_16x16x32_bf16 v[106:109], v[208:211], v[6:9], v[30:33]
	v_mfma_f32_16x16x32_bf16 v[30:33], v[26:29], v[14:17], v[74:77]
	v_mfma_f32_16x16x32_bf16 v[102:105], v[62:65], v[18:21], v[30:33]
	v_mfma_f32_16x16x32_bf16 v[30:33], v[204:207], v[14:17], v[78:81]
	v_mfma_f32_16x16x32_bf16 v[94:97], v[208:211], v[18:21], v[30:33]
	v_mfma_f32_16x16x32_bf16 v[30:33], v[26:29], v[126:129], v[82:85]
	v_mfma_f32_16x16x32_bf16 v[82:85], v[62:65], v[228:231], v[30:33]
	v_mfma_f32_16x16x32_bf16 v[30:33], v[204:207], v[126:129], v[86:89]
	v_mfma_f32_16x16x32_bf16 v[74:77], v[208:211], v[228:231], v[30:33]
	v_mfma_f32_16x16x32_bf16 v[30:33], v[26:29], v[232:235], v[90:93]
	v_mfma_f32_16x16x32_bf16 v[70:73], v[62:65], v[236:239], v[30:33]
	v_mfma_f32_16x16x32_bf16 v[30:33], v[204:207], v[232:235], v[98:101]
	v_mfma_f32_16x16x32_bf16 v[66:69], v[208:211], v[236:239], v[30:33]
	s_setprio 0
	s_setprio 1
	v_mfma_f32_16x16x32_bf16 v[30:33], v[212:215], v[2:5], v[110:113]
	v_mfma_f32_16x16x32_bf16 v[2:5], v[220:223], v[2:5], v[34:37]
	v_mfma_f32_16x16x32_bf16 v[42:45], v[224:227], v[6:9], v[2:5]
	v_mfma_f32_16x16x32_bf16 v[2:5], v[212:215], v[14:17], v[38:41]
	v_mfma_f32_16x16x32_bf16 v[38:41], v[216:219], v[18:21], v[2:5]
	v_mfma_f32_16x16x32_bf16 v[2:5], v[220:223], v[14:17], v[46:49]
	v_mfma_f32_16x16x32_bf16 v[50:53], v[216:219], v[6:9], v[30:33]
	v_mfma_f32_16x16x32_bf16 v[30:33], v[224:227], v[18:21], v[2:5]
	v_mfma_f32_16x16x32_bf16 v[2:5], v[212:215], v[126:129], v[118:121]
	v_mfma_f32_16x16x32_bf16 v[18:21], v[216:219], v[228:231], v[2:5]
	v_mfma_f32_16x16x32_bf16 v[2:5], v[220:223], v[126:129], v[240:243]
	v_mfma_f32_16x16x32_bf16 v[14:17], v[224:227], v[228:231], v[2:5]
	v_mfma_f32_16x16x32_bf16 v[2:5], v[212:215], v[232:235], v[122:125]
	v_mfma_f32_16x16x32_bf16 v[6:9], v[216:219], v[236:239], v[2:5]
	v_mfma_f32_16x16x32_bf16 v[2:5], v[220:223], v[232:235], v[58:61]
	v_mfma_f32_16x16x32_bf16 v[2:5], v[224:227], v[236:239], v[2:5]
	s_setprio 0
	s_barrier
	s_add_i32 s7, s7, s59
	v_lshl_add_u64 v[56:57], v[252:253], 0, s[24:25]
	s_mov_b32 m0, s7
	ds_read_b128 v[34:37], v150 offset:49152
	ds_read_b128 v[46:49], v150 offset:50176
	ds_read_b128 v[228:231], v150 offset:51200
	ds_read_b128 v[232:235], v150 offset:52224
	ds_read_b128 v[236:239], v150 offset:53248
	ds_read_b128 v[240:243], v150 offset:54272
	ds_read_b128 v[244:247], v150 offset:55296
	ds_read_b128 v[248:251], v150 offset:56320
	global_load_lds_dwordx4 v[56:57], off
	s_add_i32 m0, s7, 0x2000
	s_add_u32 s44, s0, 0x10180
	v_lshl_add_u64 v[56:57], v[138:139], 0, s[24:25]
	s_addc_u32 s45, s1, 0
	s_add_i32 s7, s14, s59
	global_load_lds_dwordx4 v[56:57], off
	s_mov_b32 m0, s7
	v_lshl_add_u64 v[56:57], v[140:141], 0, s[24:25]
	global_load_lds_dwordx4 v132, s[44:45]
	s_add_i32 m0, s7, 0x2000
	v_lshl_add_u64 v[54:55], v[54:55], 0, s[24:25]
	global_load_lds_dwordx4 v136, s[44:45]
	s_mov_b32 m0, s65
	s_nop 0
	global_load_lds_dwordx4 v[56:57], off
	s_mov_b32 m0, s66
	s_nop 0
	global_load_lds_dwordx4 v[54:55], off
	s_waitcnt vmcnt(8)
	s_waitcnt lgkmcnt(0)
	s_barrier
	s_setprio 1
	s_waitcnt lgkmcnt(0)
	v_mfma_f32_16x16x32_bf16 v[54:57], v[26:29], v[34:37], v[142:145]
	v_mfma_f32_16x16x32_bf16 v[126:129], v[62:65], v[46:49], v[54:57]
	v_mfma_f32_16x16x32_bf16 v[54:57], v[204:207], v[34:37], v[152:155]
	v_mfma_f32_16x16x32_bf16 v[122:125], v[208:211], v[46:49], v[54:57]
	v_mfma_f32_16x16x32_bf16 v[54:57], v[26:29], v[228:231], v[156:159]
	v_mfma_f32_16x16x32_bf16 v[118:121], v[62:65], v[232:235], v[54:57]
	v_mfma_f32_16x16x32_bf16 v[54:57], v[204:207], v[228:231], v[160:163]
	v_mfma_f32_16x16x32_bf16 v[110:113], v[208:211], v[232:235], v[54:57]
	v_mfma_f32_16x16x32_bf16 v[54:57], v[26:29], v[236:239], v[164:167]
	v_mfma_f32_16x16x32_bf16 v[98:101], v[62:65], v[240:243], v[54:57]
	v_mfma_f32_16x16x32_bf16 v[54:57], v[204:207], v[236:239], v[168:171]
	v_mfma_f32_16x16x32_bf16 v[26:29], v[26:29], v[244:247], v[172:175]
	v_mfma_f32_16x16x32_bf16 v[10:13], v[204:207], v[244:247], v[10:13]
	v_mfma_f32_16x16x32_bf16 v[90:93], v[208:211], v[240:243], v[54:57]
	v_mfma_f32_16x16x32_bf16 v[86:89], v[62:65], v[248:251], v[26:29]
	v_mfma_f32_16x16x32_bf16 v[78:81], v[208:211], v[248:251], v[10:13]
	s_setprio 0
	s_setprio 1
	v_mfma_f32_16x16x32_bf16 v[10:13], v[212:215], v[34:37], v[176:179]
	v_mfma_f32_16x16x32_bf16 v[62:65], v[216:219], v[46:49], v[10:13]
	v_mfma_f32_16x16x32_bf16 v[10:13], v[220:223], v[34:37], v[180:183]
	v_mfma_f32_16x16x32_bf16 v[58:61], v[224:227], v[46:49], v[10:13]
	v_mfma_f32_16x16x32_bf16 v[10:13], v[212:215], v[228:231], v[184:187]
	v_mfma_f32_16x16x32_bf16 v[54:57], v[216:219], v[232:235], v[10:13]
	v_mfma_f32_16x16x32_bf16 v[10:13], v[220:223], v[228:231], v[188:191]
	v_mfma_f32_16x16x32_bf16 v[46:49], v[224:227], v[232:235], v[10:13]
	v_mfma_f32_16x16x32_bf16 v[10:13], v[212:215], v[236:239], v[192:195]
	v_mfma_f32_16x16x32_bf16 v[34:37], v[216:219], v[240:243], v[10:13]
	v_mfma_f32_16x16x32_bf16 v[10:13], v[220:223], v[236:239], v[196:199]
	v_mfma_f32_16x16x32_bf16 v[26:29], v[224:227], v[240:243], v[10:13]
	v_mfma_f32_16x16x32_bf16 v[10:13], v[212:215], v[244:247], v[22:25]
	v_mfma_f32_16x16x32_bf16 v[22:25], v[216:219], v[248:251], v[10:13]
	v_mfma_f32_16x16x32_bf16 v[10:13], v[220:223], v[244:247], v[200:203]
	v_mfma_f32_16x16x32_bf16 v[10:13], v[224:227], v[248:251], v[10:13]
	s_setprio 0
	s_barrier
	s_nop 0
	s_mov_b32 s14, 2
	s_cbranch_execnz .LBB0_114

.LBB0_115:
	ds_read_b128 v[152:155], v148
	ds_read_b128 v[156:159], v148 offset:1024
	ds_read_b128 v[160:163], v148 offset:2048
	ds_read_b128 v[164:167], v148 offset:3072
	ds_read_b128 v[168:171], v149
	ds_read_b128 v[172:175], v149 offset:1024
	ds_read_b128 v[176:179], v149 offset:2048
	ds_read_b128 v[180:183], v149 offset:3072
	s_add_u32 s4, s53, s14
	s_addc_u32 s5, s80, 0
	s_add_u32 s83, s81, s14
	s_addc_u32 s85, s82, 0
	s_cmp_eq_u32 s14, s0
	s_cselect_b32 s51, s7, s5
	s_cselect_b32 s50, s43, s4
	s_cselect_b32 s5, s41, s85
	s_cselect_b32 s4, s49, s83
	s_add_i32 s85, s60, 0xc000
	v_lshl_add_u64 v[138:139], v[142:143], 0, s[14:15]
	s_mov_b32 m0, s85
	s_add_i32 s83, s60, 0xe000
	ds_read_b128 v[184:187], v150
	ds_read_b128 v[188:191], v150 offset:1024
	ds_read_b128 v[192:195], v150 offset:2048
	ds_read_b128 v[196:199], v150 offset:3072
	ds_read_b128 v[200:203], v150 offset:4096
	ds_read_b128 v[204:207], v150 offset:5120
	ds_read_b128 v[208:211], v150 offset:6144
	ds_read_b128 v[212:215], v150 offset:7168
	global_load_lds_dwordx4 v[138:139], off
	v_lshl_add_u64 v[138:139], v[144:145], 0, s[14:15]
	s_mov_b32 m0, s83
	s_nop 0
	global_load_lds_dwordx4 v[138:139], off
	s_waitcnt vmcnt(8)
	s_waitcnt lgkmcnt(0)
	s_barrier
	s_setprio 1
	s_waitcnt lgkmcnt(0)
	s_nop 0
	v_mfma_f32_16x16x32_bf16 v[114:117], v[152:155], v[184:187], v[114:117]
	v_mfma_f32_16x16x32_bf16 v[106:109], v[160:163], v[184:187], v[106:109]
	v_mfma_f32_16x16x32_bf16 v[102:105], v[152:155], v[192:195], v[102:105]
	v_mfma_f32_16x16x32_bf16 v[94:97], v[160:163], v[192:195], v[94:97]
	v_mfma_f32_16x16x32_bf16 v[82:85], v[152:155], v[200:203], v[82:85]
	v_mfma_f32_16x16x32_bf16 v[74:77], v[160:163], v[200:203], v[74:77]
	v_mfma_f32_16x16x32_bf16 v[70:73], v[152:155], v[208:211], v[70:73]
	v_mfma_f32_16x16x32_bf16 v[66:69], v[160:163], v[208:211], v[66:69]
	v_mfma_f32_16x16x32_bf16 v[114:117], v[156:159], v[188:191], v[114:117]
	v_mfma_f32_16x16x32_bf16 v[106:109], v[164:167], v[188:191], v[106:109]
	v_mfma_f32_16x16x32_bf16 v[102:105], v[156:159], v[196:199], v[102:105]
	v_mfma_f32_16x16x32_bf16 v[94:97], v[164:167], v[196:199], v[94:97]
	v_mfma_f32_16x16x32_bf16 v[82:85], v[156:159], v[204:207], v[82:85]
	v_mfma_f32_16x16x32_bf16 v[74:77], v[164:167], v[204:207], v[74:77]
	v_mfma_f32_16x16x32_bf16 v[70:73], v[156:159], v[212:215], v[70:73]
	v_mfma_f32_16x16x32_bf16 v[66:69], v[164:167], v[212:215], v[66:69]
	s_setprio 0
	s_setprio 1
	v_mfma_f32_16x16x32_bf16 v[50:53], v[168:171], v[184:187], v[50:53]
	v_mfma_f32_16x16x32_bf16 v[42:45], v[176:179], v[184:187], v[42:45]
	v_mfma_f32_16x16x32_bf16 v[38:41], v[168:171], v[192:195], v[38:41]
	v_mfma_f32_16x16x32_bf16 v[30:33], v[176:179], v[192:195], v[30:33]
	v_mfma_f32_16x16x32_bf16 v[18:21], v[168:171], v[200:203], v[18:21]
	v_mfma_f32_16x16x32_bf16 v[14:17], v[176:179], v[200:203], v[14:17]
	v_mfma_f32_16x16x32_bf16 v[6:9], v[168:171], v[208:211], v[6:9]
	v_mfma_f32_16x16x32_bf16 v[2:5], v[176:179], v[208:211], v[2:5]
	v_mfma_f32_16x16x32_bf16 v[50:53], v[172:175], v[188:191], v[50:53]
	v_mfma_f32_16x16x32_bf16 v[42:45], v[180:183], v[188:191], v[42:45]
	v_mfma_f32_16x16x32_bf16 v[38:41], v[172:175], v[196:199], v[38:41]
	v_mfma_f32_16x16x32_bf16 v[30:33], v[180:183], v[196:199], v[30:33]
	v_mfma_f32_16x16x32_bf16 v[18:21], v[172:175], v[204:207], v[18:21]
	v_mfma_f32_16x16x32_bf16 v[14:17], v[180:183], v[204:207], v[14:17]
	v_mfma_f32_16x16x32_bf16 v[6:9], v[172:175], v[212:215], v[6:9]
	v_mfma_f32_16x16x32_bf16 v[2:5], v[180:183], v[212:215], v[2:5]
	s_setprio 0
	s_barrier
	s_add_i32 s86, s75, s59
	v_lshl_add_u64 v[138:139], s[4:5], 0, v[132:133]
	s_mov_b32 m0, s86
	ds_read_b128 v[184:187], v150 offset:16384
	ds_read_b128 v[188:191], v150 offset:17408
	ds_read_b128 v[192:195], v150 offset:18432
	ds_read_b128 v[196:199], v150 offset:19456
	ds_read_b128 v[200:203], v150 offset:20480
	ds_read_b128 v[204:207], v150 offset:21504
	ds_read_b128 v[208:211], v150 offset:22528
	ds_read_b128 v[212:215], v150 offset:23552
	global_load_lds_dwordx4 v[138:139], off
	s_add_i32 m0, s86, 0x2000
	s_add_u32 s86, s4, 0x10000
	v_lshl_add_u64 v[140:141], s[4:5], 0, v[136:137]
	s_addc_u32 s87, s5, 0
	s_add_i32 s88, s76, s59
	global_load_lds_dwordx4 v[140:141], off
	v_lshl_add_u64 v[216:217], s[86:87], 0, v[132:133]
	s_mov_b32 m0, s88
	v_lshl_add_u64 v[218:219], s[50:51], 0, v[134:135]
	global_load_lds_dwordx4 v[216:217], off
	v_lshl_add_u64 v[216:217], s[86:87], 0, v[136:137]
	s_add_i32 m0, s88, 0x2000
	s_nop 0
	global_load_lds_dwordx4 v[216:217], off
	v_lshl_add_u64 v[216:217], s[50:51], 0, v[130:131]
	s_mov_b32 m0, s60
	s_nop 0
	global_load_lds_dwordx4 v[216:217], off
	s_mov_b32 m0, s61
	s_nop 0
	global_load_lds_dwordx4 v[218:219], off
	s_waitcnt vmcnt(8)
	s_waitcnt lgkmcnt(0)
	s_barrier
	s_setprio 1
	s_waitcnt lgkmcnt(0)
	s_nop 0
	v_mfma_f32_16x16x32_bf16 v[126:129], v[152:155], v[184:187], v[126:129]
	v_mfma_f32_16x16x32_bf16 v[122:125], v[160:163], v[184:187], v[122:125]
	v_mfma_f32_16x16x32_bf16 v[118:121], v[152:155], v[192:195], v[118:121]
	v_mfma_f32_16x16x32_bf16 v[110:113], v[160:163], v[192:195], v[110:113]
	v_mfma_f32_16x16x32_bf16 v[98:101], v[152:155], v[200:203], v[98:101]
	v_mfma_f32_16x16x32_bf16 v[90:93], v[160:163], v[200:203], v[90:93]
	v_mfma_f32_16x16x32_bf16 v[86:89], v[152:155], v[208:211], v[86:89]
	v_mfma_f32_16x16x32_bf16 v[78:81], v[160:163], v[208:211], v[78:81]
	v_mfma_f32_16x16x32_bf16 v[126:129], v[156:159], v[188:191], v[126:129]
	v_mfma_f32_16x16x32_bf16 v[122:125], v[164:167], v[188:191], v[122:125]
	v_mfma_f32_16x16x32_bf16 v[118:121], v[156:159], v[196:199], v[118:121]
	v_mfma_f32_16x16x32_bf16 v[110:113], v[164:167], v[196:199], v[110:113]
	v_mfma_f32_16x16x32_bf16 v[98:101], v[156:159], v[204:207], v[98:101]
	v_mfma_f32_16x16x32_bf16 v[90:93], v[164:167], v[204:207], v[90:93]
	v_mfma_f32_16x16x32_bf16 v[86:89], v[156:159], v[212:215], v[86:89]
	v_mfma_f32_16x16x32_bf16 v[78:81], v[164:167], v[212:215], v[78:81]
	s_setprio 0
	s_setprio 1
	v_mfma_f32_16x16x32_bf16 v[62:65], v[168:171], v[184:187], v[62:65]
	v_mfma_f32_16x16x32_bf16 v[58:61], v[176:179], v[184:187], v[58:61]
	v_mfma_f32_16x16x32_bf16 v[54:57], v[168:171], v[192:195], v[54:57]
	v_mfma_f32_16x16x32_bf16 v[46:49], v[176:179], v[192:195], v[46:49]
	v_mfma_f32_16x16x32_bf16 v[34:37], v[168:171], v[200:203], v[34:37]
	v_mfma_f32_16x16x32_bf16 v[26:29], v[176:179], v[200:203], v[26:29]
	v_mfma_f32_16x16x32_bf16 v[22:25], v[168:171], v[208:211], v[22:25]
	v_mfma_f32_16x16x32_bf16 v[10:13], v[176:179], v[208:211], v[10:13]
	v_mfma_f32_16x16x32_bf16 v[62:65], v[172:175], v[188:191], v[62:65]
	v_mfma_f32_16x16x32_bf16 v[58:61], v[180:183], v[188:191], v[58:61]
	v_mfma_f32_16x16x32_bf16 v[54:57], v[172:175], v[196:199], v[54:57]
	v_mfma_f32_16x16x32_bf16 v[46:49], v[180:183], v[196:199], v[46:49]
	v_mfma_f32_16x16x32_bf16 v[34:37], v[172:175], v[204:207], v[34:37]
	v_mfma_f32_16x16x32_bf16 v[26:29], v[180:183], v[204:207], v[26:29]
	v_mfma_f32_16x16x32_bf16 v[22:25], v[172:175], v[212:215], v[22:25]
	v_mfma_f32_16x16x32_bf16 v[10:13], v[180:183], v[212:215], v[10:13]
	s_setprio 0
	s_barrier
	s_add_i32 s86, 0, 0x18000
	s_add_i32 s87, 0, 0x1c000
	v_add_u32_e32 v164, s86, v147
	v_add_u32_e32 v180, s87, v147
	ds_read_b128 v[152:155], v164
	ds_read_b128 v[156:159], v164 offset:1024
	ds_read_b128 v[160:163], v164 offset:2048
	ds_read_b128 v[164:167], v164 offset:3072
	ds_read_b128 v[168:171], v180
	ds_read_b128 v[172:175], v180 offset:1024
	ds_read_b128 v[176:179], v180 offset:2048
	ds_read_b128 v[180:183], v180 offset:3072
	s_add_u32 s50, s50, 0x40000
	s_addc_u32 s51, s51, 0
	s_mov_b32 m0, s62
	v_lshl_add_u64 v[220:221], s[50:51], 0, v[130:131]
	ds_read_b128 v[184:187], v150 offset:32768
	ds_read_b128 v[188:191], v150 offset:33792
	ds_read_b128 v[192:195], v150 offset:34816
	ds_read_b128 v[196:199], v150 offset:35840
	ds_read_b128 v[200:203], v150 offset:36864
	ds_read_b128 v[204:207], v150 offset:37888
	ds_read_b128 v[208:211], v150 offset:38912
	ds_read_b128 v[212:215], v150 offset:39936
	global_load_lds_dwordx4 v[220:221], off
	v_lshl_add_u64 v[220:221], s[50:51], 0, v[134:135]
	s_mov_b32 m0, s63
	s_nop 0
	global_load_lds_dwordx4 v[220:221], off
	s_waitcnt vmcnt(8)
	s_waitcnt lgkmcnt(0)
	s_barrier
	s_setprio 1
	s_waitcnt lgkmcnt(0)
	s_nop 0
	v_mfma_f32_16x16x32_bf16 v[114:117], v[152:155], v[184:187], v[114:117]
	v_mfma_f32_16x16x32_bf16 v[106:109], v[160:163], v[184:187], v[106:109]
	v_mfma_f32_16x16x32_bf16 v[102:105], v[152:155], v[192:195], v[102:105]
	v_mfma_f32_16x16x32_bf16 v[94:97], v[160:163], v[192:195], v[94:97]
	v_mfma_f32_16x16x32_bf16 v[82:85], v[152:155], v[200:203], v[82:85]
	v_mfma_f32_16x16x32_bf16 v[74:77], v[160:163], v[200:203], v[74:77]
	v_mfma_f32_16x16x32_bf16 v[70:73], v[152:155], v[208:211], v[70:73]
	v_mfma_f32_16x16x32_bf16 v[66:69], v[160:163], v[208:211], v[66:69]
	v_mfma_f32_16x16x32_bf16 v[114:117], v[156:159], v[188:191], v[114:117]
	v_mfma_f32_16x16x32_bf16 v[106:109], v[164:167], v[188:191], v[106:109]
	v_mfma_f32_16x16x32_bf16 v[102:105], v[156:159], v[196:199], v[102:105]
	v_mfma_f32_16x16x32_bf16 v[94:97], v[164:167], v[196:199], v[94:97]
	v_mfma_f32_16x16x32_bf16 v[82:85], v[156:159], v[204:207], v[82:85]
	v_mfma_f32_16x16x32_bf16 v[74:77], v[164:167], v[204:207], v[74:77]
	v_mfma_f32_16x16x32_bf16 v[70:73], v[156:159], v[212:215], v[70:73]
	v_mfma_f32_16x16x32_bf16 v[66:69], v[164:167], v[212:215], v[66:69]
	s_setprio 0
	s_setprio 1
	v_mfma_f32_16x16x32_bf16 v[50:53], v[168:171], v[184:187], v[50:53]
	v_mfma_f32_16x16x32_bf16 v[42:45], v[176:179], v[184:187], v[42:45]
	v_mfma_f32_16x16x32_bf16 v[38:41], v[168:171], v[192:195], v[38:41]
	v_mfma_f32_16x16x32_bf16 v[30:33], v[176:179], v[192:195], v[30:33]
	v_mfma_f32_16x16x32_bf16 v[18:21], v[168:171], v[200:203], v[18:21]
	v_mfma_f32_16x16x32_bf16 v[14:17], v[176:179], v[200:203], v[14:17]
	v_mfma_f32_16x16x32_bf16 v[6:9], v[168:171], v[208:211], v[6:9]
	v_mfma_f32_16x16x32_bf16 v[2:5], v[176:179], v[208:211], v[2:5]
	v_mfma_f32_16x16x32_bf16 v[50:53], v[172:175], v[188:191], v[50:53]
	v_mfma_f32_16x16x32_bf16 v[42:45], v[180:183], v[188:191], v[42:45]
	v_mfma_f32_16x16x32_bf16 v[38:41], v[172:175], v[196:199], v[38:41]
	v_mfma_f32_16x16x32_bf16 v[30:33], v[180:183], v[196:199], v[30:33]
	v_mfma_f32_16x16x32_bf16 v[18:21], v[172:175], v[204:207], v[18:21]
	v_mfma_f32_16x16x32_bf16 v[14:17], v[180:183], v[204:207], v[14:17]
	v_mfma_f32_16x16x32_bf16 v[6:9], v[172:175], v[212:215], v[6:9]
	v_mfma_f32_16x16x32_bf16 v[2:5], v[180:183], v[212:215], v[2:5]
	s_setprio 0
	s_barrier
	s_add_i32 s50, s86, s59
	v_lshl_add_u64 v[138:139], v[138:139], 0, s[18:19]
	s_mov_b32 m0, s50
	ds_read_b128 v[184:187], v150 offset:49152
	ds_read_b128 v[188:191], v150 offset:50176
	ds_read_b128 v[192:195], v150 offset:51200
	ds_read_b128 v[196:199], v150 offset:52224
	ds_read_b128 v[200:203], v150 offset:53248
	ds_read_b128 v[204:207], v150 offset:54272
	ds_read_b128 v[208:211], v150 offset:55296
	ds_read_b128 v[212:215], v150 offset:56320
	global_load_lds_dwordx4 v[138:139], off
	s_add_i32 m0, s50, 0x2000
	s_add_u32 s4, s4, 0x10080
	v_lshl_add_u64 v[138:139], v[140:141], 0, s[18:19]
	s_addc_u32 s5, s5, 0
	s_add_i32 s50, s87, s59
	global_load_lds_dwordx4 v[138:139], off
	v_lshl_add_u64 v[138:139], s[4:5], 0, v[132:133]
	s_mov_b32 m0, s50
	s_nop 0
	global_load_lds_dwordx4 v[138:139], off
	v_lshl_add_u64 v[138:139], s[4:5], 0, v[136:137]
	s_add_i32 m0, s50, 0x2000
	s_nop 0
	global_load_lds_dwordx4 v[138:139], off
	v_lshl_add_u64 v[138:139], v[216:217], 0, s[18:19]
	s_mov_b32 m0, s65
	s_nop 0
	global_load_lds_dwordx4 v[138:139], off
	v_lshl_add_u64 v[138:139], v[218:219], 0, s[18:19]
	s_mov_b32 m0, s66
	s_nop 0
	global_load_lds_dwordx4 v[138:139], off
	s_waitcnt vmcnt(8)
	s_waitcnt lgkmcnt(0)
	s_barrier
	s_setprio 1
	s_waitcnt lgkmcnt(0)
	v_mfma_f32_16x16x32_bf16 v[126:129], v[152:155], v[184:187], v[126:129]
	v_mfma_f32_16x16x32_bf16 v[122:125], v[160:163], v[184:187], v[122:125]
	v_mfma_f32_16x16x32_bf16 v[118:121], v[152:155], v[192:195], v[118:121]
	v_mfma_f32_16x16x32_bf16 v[110:113], v[160:163], v[192:195], v[110:113]
	v_mfma_f32_16x16x32_bf16 v[98:101], v[152:155], v[200:203], v[98:101]
	v_mfma_f32_16x16x32_bf16 v[90:93], v[160:163], v[200:203], v[90:93]
	v_mfma_f32_16x16x32_bf16 v[86:89], v[152:155], v[208:211], v[86:89]
	v_mfma_f32_16x16x32_bf16 v[78:81], v[160:163], v[208:211], v[78:81]
	v_mfma_f32_16x16x32_bf16 v[126:129], v[156:159], v[188:191], v[126:129]
	v_mfma_f32_16x16x32_bf16 v[122:125], v[164:167], v[188:191], v[122:125]
	v_mfma_f32_16x16x32_bf16 v[118:121], v[156:159], v[196:199], v[118:121]
	v_mfma_f32_16x16x32_bf16 v[110:113], v[164:167], v[196:199], v[110:113]
	v_mfma_f32_16x16x32_bf16 v[98:101], v[156:159], v[204:207], v[98:101]
	v_mfma_f32_16x16x32_bf16 v[90:93], v[164:167], v[204:207], v[90:93]
	v_mfma_f32_16x16x32_bf16 v[86:89], v[156:159], v[212:215], v[86:89]
	v_mfma_f32_16x16x32_bf16 v[78:81], v[164:167], v[212:215], v[78:81]
	s_setprio 0
	s_setprio 1
	v_mfma_f32_16x16x32_bf16 v[62:65], v[168:171], v[184:187], v[62:65]
	v_mfma_f32_16x16x32_bf16 v[58:61], v[176:179], v[184:187], v[58:61]
	v_mfma_f32_16x16x32_bf16 v[54:57], v[168:171], v[192:195], v[54:57]
	v_mfma_f32_16x16x32_bf16 v[46:49], v[176:179], v[192:195], v[46:49]
	v_mfma_f32_16x16x32_bf16 v[34:37], v[168:171], v[200:203], v[34:37]
	v_mfma_f32_16x16x32_bf16 v[26:29], v[176:179], v[200:203], v[26:29]
	v_mfma_f32_16x16x32_bf16 v[22:25], v[168:171], v[208:211], v[22:25]
	v_mfma_f32_16x16x32_bf16 v[10:13], v[176:179], v[208:211], v[10:13]
	v_mfma_f32_16x16x32_bf16 v[62:65], v[172:175], v[188:191], v[62:65]
	v_mfma_f32_16x16x32_bf16 v[58:61], v[180:183], v[188:191], v[58:61]
	v_mfma_f32_16x16x32_bf16 v[54:57], v[172:175], v[196:199], v[54:57]
	v_mfma_f32_16x16x32_bf16 v[46:49], v[180:183], v[196:199], v[46:49]
	v_mfma_f32_16x16x32_bf16 v[34:37], v[172:175], v[204:207], v[34:37]
	v_mfma_f32_16x16x32_bf16 v[26:29], v[180:183], v[204:207], v[26:29]
	v_mfma_f32_16x16x32_bf16 v[22:25], v[172:175], v[212:215], v[22:25]
	v_mfma_f32_16x16x32_bf16 v[10:13], v[180:183], v[212:215], v[10:13]
	s_setprio 0
	s_barrier
	s_nop 0
	s_add_i32 s52, s52, 2
	s_add_u32 s53, s53, 0x100
	s_addc_u32 s80, s80, 0
	s_add_u32 s81, s81, 0x100
	s_addc_u32 s82, s82, 0
	s_add_u32 s0, s0, 0xffffff00
	s_addc_u32 s1, s1, -1
	v_lshl_add_u64 v[142:143], v[142:143], 0, s[22:23]
	s_cmp_gt_u32 s52, 13
	v_lshl_add_u64 v[144:145], v[144:145], 0, s[22:23]
	s_cbranch_scc0 .LBB0_115
	s_add_u32 s0, s43, 0x40080
	s_addc_u32 s1, s7, 0
	s_mov_b32 m0, s85
	v_lshl_add_u64 v[138:139], s[0:1], 0, v[130:131]
	global_load_lds_dwordx4 v[138:139], off
	v_lshl_add_u64 v[138:139], s[0:1], 0, v[134:135]
	s_mov_b32 m0, s83
	s_and_b64 vcc, exec, s[20:21]
	global_load_lds_dwordx4 v[138:139], off
	s_cbranch_vccz .LBB0_118
	s_barrier

.LBB0_685:
	s_cmp_lg_u32 s5, 0
	v_mov_b32_e32 v137, v141
	v_mov_b32_e32 v139, v141
	v_mov_b32_e32 v135, v141
	s_cbranch_scc0 .LBB0_699
	ds_read_b128 v[2:5], v160
	ds_read_b128 v[6:9], v160 offset:1024
	ds_read_b128 v[10:13], v160 offset:2048
	ds_read_b128 v[14:17], v160 offset:3072
	ds_read_b128 v[18:21], v161
	ds_read_b128 v[22:25], v161 offset:1024
	ds_read_b128 v[26:29], v161 offset:2048
	ds_read_b128 v[30:33], v161 offset:3072
	ds_read_b128 v[34:37], v162
	ds_read_b128 v[38:41], v162 offset:1024
	ds_read_b128 v[42:45], v162 offset:2048
	ds_read_b128 v[46:49], v162 offset:3072
	ds_read_b128 v[50:53], v162 offset:4096
	ds_read_b128 v[54:57], v162 offset:5120
	ds_read_b128 v[58:61], v162 offset:6144
	ds_read_b128 v[62:65], v162 offset:7168
	s_waitcnt vmcnt(24)
	s_waitcnt lgkmcnt(0)
	s_barrier
	s_setprio 1
	s_waitcnt lgkmcnt(0)
	s_nop 0
	v_mfma_f32_16x16x32_bf16 v[90:93], v[2:5], v[58:61], 0
	v_mfma_f32_16x16x32_bf16 v[66:69], v[2:5], v[34:37], 0
	v_mfma_f32_16x16x32_bf16 v[70:73], v[10:13], v[34:37], 0
	v_mfma_f32_16x16x32_bf16 v[74:77], v[2:5], v[42:45], 0
	v_mfma_f32_16x16x32_bf16 v[78:81], v[10:13], v[42:45], 0
	v_mfma_f32_16x16x32_bf16 v[82:85], v[2:5], v[50:53], 0
	v_mfma_f32_16x16x32_bf16 v[86:89], v[10:13], v[50:53], 0
	v_mfma_f32_16x16x32_bf16 v[98:101], v[6:9], v[62:65], v[90:93]
	v_mfma_f32_16x16x32_bf16 v[90:93], v[10:13], v[58:61], 0
	v_mfma_f32_16x16x32_bf16 v[66:69], v[6:9], v[38:41], v[66:69]
	v_mfma_f32_16x16x32_bf16 v[70:73], v[14:17], v[38:41], v[70:73]
	v_mfma_f32_16x16x32_bf16 v[74:77], v[6:9], v[46:49], v[74:77]
	v_mfma_f32_16x16x32_bf16 v[78:81], v[14:17], v[46:49], v[78:81]
	v_mfma_f32_16x16x32_bf16 v[82:85], v[6:9], v[54:57], v[82:85]
	v_mfma_f32_16x16x32_bf16 v[86:89], v[14:17], v[54:57], v[86:89]
	v_mfma_f32_16x16x32_bf16 v[102:105], v[14:17], v[62:65], v[90:93]
	s_setprio 0
	s_setprio 1
	v_mfma_f32_16x16x32_bf16 v[90:93], v[18:21], v[34:37], 0
	v_mfma_f32_16x16x32_bf16 v[34:37], v[26:29], v[34:37], 0
	v_mfma_f32_16x16x32_bf16 v[114:117], v[22:25], v[38:41], v[90:93]
	v_mfma_f32_16x16x32_bf16 v[34:37], v[30:33], v[38:41], v[34:37]
	v_mfma_f32_16x16x32_bf16 v[38:41], v[18:21], v[42:45], 0
	v_mfma_f32_16x16x32_bf16 v[42:45], v[26:29], v[42:45], 0
	v_mfma_f32_16x16x32_bf16 v[38:41], v[22:25], v[46:49], v[38:41]
	v_mfma_f32_16x16x32_bf16 v[42:45], v[30:33], v[46:49], v[42:45]
	v_mfma_f32_16x16x32_bf16 v[46:49], v[18:21], v[50:53], 0
	v_mfma_f32_16x16x32_bf16 v[50:53], v[26:29], v[50:53], 0
	v_mfma_f32_16x16x32_bf16 v[46:49], v[22:25], v[54:57], v[46:49]
	v_mfma_f32_16x16x32_bf16 v[50:53], v[30:33], v[54:57], v[50:53]
	v_mfma_f32_16x16x32_bf16 v[54:57], v[18:21], v[58:61], 0
	v_mfma_f32_16x16x32_bf16 v[58:61], v[26:29], v[58:61], 0
	v_mfma_f32_16x16x32_bf16 v[54:57], v[22:25], v[62:65], v[54:57]
	v_mfma_f32_16x16x32_bf16 v[58:61], v[30:33], v[62:65], v[58:61]
	s_setprio 0
	s_barrier
	v_lshl_add_u64 v[244:245], s[0:1], 0, v[136:137]
	s_add_i32 s5, s69, s55
	v_lshl_add_u64 v[130:131], v[244:245], 0, s[18:19]
	s_mov_b32 m0, s5
	ds_read_b128 v[62:65], v162 offset:16384
	ds_read_b128 v[90:93], v162 offset:17408
	ds_read_b128 v[94:97], v162 offset:18432
	ds_read_b128 v[106:109], v162 offset:19456
	ds_read_b128 v[110:113], v162 offset:20480
	ds_read_b128 v[118:121], v162 offset:21504
	ds_read_b128 v[122:125], v162 offset:22528
	ds_read_b128 v[126:129], v162 offset:23552
	global_load_lds_dwordx4 v[130:131], off
	s_add_i32 m0, s5, 0x2000
	v_lshl_add_u64 v[246:247], s[0:1], 0, v[140:141]
	s_add_u32 s44, s0, 0x40100
	v_lshl_add_u64 v[130:131], v[246:247], 0, s[18:19]
	s_addc_u32 s45, s1, 0
	s_add_i32 s5, s70, s55
	global_load_lds_dwordx4 v[130:131], off
	s_mov_b32 m0, s5
	v_lshl_add_u64 v[248:249], s[48:49], 0, v[134:135]
	global_load_lds_dwordx4 v136, s[44:45]
	s_add_i32 m0, s5, 0x2000
	v_lshl_add_u64 v[130:131], v[248:249], 0, s[18:19]
	global_load_lds_dwordx4 v140, s[44:45]
	s_mov_b32 m0, s56
	v_lshl_add_u64 v[250:251], s[48:49], 0, v[138:139]
	global_load_lds_dwordx4 v[130:131], off
	v_lshl_add_u64 v[130:131], v[250:251], 0, s[18:19]
	s_mov_b32 m0, s57
	s_nop 0
	global_load_lds_dwordx4 v[130:131], off
	s_waitcnt vmcnt(24)
	s_waitcnt lgkmcnt(0)
	s_barrier
	s_setprio 1
	s_waitcnt lgkmcnt(0)
	s_nop 0
	v_mfma_f32_16x16x32_bf16 v[130:133], v[2:5], v[62:65], 0
	v_mfma_f32_16x16x32_bf16 v[150:153], v[2:5], v[94:97], 0
	v_mfma_f32_16x16x32_bf16 v[164:167], v[2:5], v[110:113], 0
	v_mfma_f32_16x16x32_bf16 v[2:5], v[2:5], v[122:125], 0
	v_mfma_f32_16x16x32_bf16 v[172:175], v[6:9], v[126:129], v[2:5]
	v_mfma_f32_16x16x32_bf16 v[2:5], v[10:13], v[122:125], 0
	v_mfma_f32_16x16x32_bf16 v[146:149], v[10:13], v[62:65], 0
	v_mfma_f32_16x16x32_bf16 v[154:157], v[10:13], v[94:97], 0
	v_mfma_f32_16x16x32_bf16 v[168:171], v[10:13], v[110:113], 0
	v_mfma_f32_16x16x32_bf16 v[10:13], v[14:17], v[126:129], v[2:5]
	v_mfma_f32_16x16x32_bf16 v[130:133], v[6:9], v[90:93], v[130:133]
	v_mfma_f32_16x16x32_bf16 v[146:149], v[14:17], v[90:93], v[146:149]
	v_mfma_f32_16x16x32_bf16 v[150:153], v[6:9], v[106:109], v[150:153]
	v_mfma_f32_16x16x32_bf16 v[154:157], v[14:17], v[106:109], v[154:157]
	v_mfma_f32_16x16x32_bf16 v[164:167], v[6:9], v[118:121], v[164:167]
	v_mfma_f32_16x16x32_bf16 v[168:171], v[14:17], v[118:121], v[168:171]
	s_setprio 0
	s_setprio 1
	v_mfma_f32_16x16x32_bf16 v[2:5], v[18:21], v[62:65], 0
	v_mfma_f32_16x16x32_bf16 v[14:17], v[22:25], v[90:93], v[2:5]
	v_mfma_f32_16x16x32_bf16 v[2:5], v[26:29], v[62:65], 0
	v_mfma_f32_16x16x32_bf16 v[176:179], v[30:33], v[90:93], v[2:5]
	v_mfma_f32_16x16x32_bf16 v[2:5], v[18:21], v[94:97], 0
	v_mfma_f32_16x16x32_bf16 v[180:183], v[22:25], v[106:109], v[2:5]
	v_mfma_f32_16x16x32_bf16 v[2:5], v[26:29], v[94:97], 0
	v_mfma_f32_16x16x32_bf16 v[184:187], v[30:33], v[106:109], v[2:5]
	v_mfma_f32_16x16x32_bf16 v[2:5], v[18:21], v[110:113], 0
	v_mfma_f32_16x16x32_bf16 v[188:191], v[22:25], v[118:121], v[2:5]
	v_mfma_f32_16x16x32_bf16 v[2:5], v[26:29], v[110:113], 0
	v_mfma_f32_16x16x32_bf16 v[192:195], v[30:33], v[118:121], v[2:5]
	v_mfma_f32_16x16x32_bf16 v[2:5], v[18:21], v[122:125], 0
	v_mfma_f32_16x16x32_bf16 v[196:199], v[22:25], v[126:129], v[2:5]
	v_mfma_f32_16x16x32_bf16 v[2:5], v[26:29], v[122:125], 0
	v_mfma_f32_16x16x32_bf16 v[26:29], v[30:33], v[126:129], v[2:5]
	s_setprio 0
	s_barrier
	s_add_i32 s5, 0, 0x18000
	s_nop 3
	v_add_u32_e32 v2, s5, v159
	s_add_i32 s10, 0, 0x1c000
	ds_read_b128 v[18:21], v2
	ds_read_b128 v[22:25], v2 offset:1024
	ds_read_b128 v[30:33], v2 offset:2048
	ds_read_b128 v[200:203], v2 offset:3072
	v_add_u32_e32 v2, s10, v159
	ds_read_b128 v[204:207], v2
	ds_read_b128 v[208:211], v2 offset:1024
	ds_read_b128 v[212:215], v2 offset:2048
	ds_read_b128 v[216:219], v2 offset:3072
	s_add_u32 s44, s48, 0x40100
	s_addc_u32 s45, s49, 0
	s_mov_b32 m0, s58
	ds_read_b128 v[2:5], v162 offset:32768
	ds_read_b128 v[6:9], v162 offset:33792
	ds_read_b128 v[62:65], v162 offset:34816
	ds_read_b128 v[220:223], v162 offset:35840
	ds_read_b128 v[224:227], v162 offset:36864
	ds_read_b128 v[228:231], v162 offset:37888
	ds_read_b128 v[232:235], v162 offset:38912
	ds_read_b128 v[236:239], v162 offset:39936
	global_load_lds_dwordx4 v134, s[44:45]
	s_mov_b32 m0, s59
	s_nop 0
	global_load_lds_dwordx4 v138, s[44:45]
	s_waitcnt vmcnt(24)
	s_waitcnt lgkmcnt(0)
	s_barrier
	s_setprio 1
	s_waitcnt lgkmcnt(0)
	v_mfma_f32_16x16x32_bf16 v[66:69], v[18:21], v[2:5], v[66:69]
	v_mfma_f32_16x16x32_bf16 v[126:129], v[22:25], v[6:9], v[66:69]
	v_mfma_f32_16x16x32_bf16 v[66:69], v[30:33], v[2:5], v[70:73]
	v_mfma_f32_16x16x32_bf16 v[122:125], v[200:203], v[6:9], v[66:69]
	v_mfma_f32_16x16x32_bf16 v[66:69], v[18:21], v[62:65], v[74:77]
	v_mfma_f32_16x16x32_bf16 v[110:113], v[22:25], v[220:223], v[66:69]
	v_mfma_f32_16x16x32_bf16 v[66:69], v[30:33], v[62:65], v[78:81]
	v_mfma_f32_16x16x32_bf16 v[106:109], v[200:203], v[220:223], v[66:69]
	v_mfma_f32_16x16x32_bf16 v[66:69], v[18:21], v[224:227], v[82:85]
	v_mfma_f32_16x16x32_bf16 v[94:97], v[22:25], v[228:231], v[66:69]
	v_mfma_f32_16x16x32_bf16 v[66:69], v[30:33], v[224:227], v[86:89]
	v_mfma_f32_16x16x32_bf16 v[90:93], v[200:203], v[228:231], v[66:69]
	v_mfma_f32_16x16x32_bf16 v[66:69], v[18:21], v[232:235], v[98:101]
	v_mfma_f32_16x16x32_bf16 v[78:81], v[22:25], v[236:239], v[66:69]
	v_mfma_f32_16x16x32_bf16 v[66:69], v[30:33], v[232:235], v[102:105]
	v_mfma_f32_16x16x32_bf16 v[74:77], v[200:203], v[236:239], v[66:69]
	s_setprio 0
	s_setprio 1
	v_mfma_f32_16x16x32_bf16 v[66:69], v[204:207], v[2:5], v[114:117]
	v_mfma_f32_16x16x32_bf16 v[2:5], v[212:215], v[2:5], v[34:37]
	v_mfma_f32_16x16x32_bf16 v[114:117], v[216:219], v[6:9], v[2:5]
	v_mfma_f32_16x16x32_bf16 v[2:5], v[204:207], v[62:65], v[38:41]
	v_mfma_f32_16x16x32_bf16 v[102:105], v[208:211], v[220:223], v[2:5]
	v_mfma_f32_16x16x32_bf16 v[2:5], v[212:215], v[62:65], v[42:45]
	v_mfma_f32_16x16x32_bf16 v[98:101], v[216:219], v[220:223], v[2:5]
	v_mfma_f32_16x16x32_bf16 v[2:5], v[204:207], v[224:227], v[46:49]
	v_mfma_f32_16x16x32_bf16 v[86:89], v[208:211], v[228:231], v[2:5]
	v_mfma_f32_16x16x32_bf16 v[2:5], v[212:215], v[224:227], v[50:53]
	v_mfma_f32_16x16x32_bf16 v[82:85], v[216:219], v[228:231], v[2:5]
	v_mfma_f32_16x16x32_bf16 v[2:5], v[204:207], v[232:235], v[54:57]
	v_mfma_f32_16x16x32_bf16 v[70:73], v[208:211], v[236:239], v[2:5]
	v_mfma_f32_16x16x32_bf16 v[2:5], v[212:215], v[232:235], v[58:61]
	v_mfma_f32_16x16x32_bf16 v[118:121], v[208:211], v[6:9], v[66:69]
	v_mfma_f32_16x16x32_bf16 v[66:69], v[216:219], v[236:239], v[2:5]
	s_setprio 0
	s_barrier
	s_add_i32 s5, s5, s55
	s_nop 2
	v_lshl_add_u64 v[2:3], v[244:245], 0, s[20:21]
	s_mov_b32 m0, s5
	ds_read_b128 v[34:37], v162 offset:49152
	ds_read_b128 v[38:41], v162 offset:50176
	ds_read_b128 v[220:223], v162 offset:51200
	ds_read_b128 v[224:227], v162 offset:52224
	ds_read_b128 v[228:231], v162 offset:53248
	ds_read_b128 v[232:235], v162 offset:54272
	ds_read_b128 v[236:239], v162 offset:55296
	ds_read_b128 v[240:243], v162 offset:56320
	global_load_lds_dwordx4 v[2:3], off
	s_add_i32 m0, s5, 0x2000
	s_add_u32 s44, s0, 0x40180
	v_lshl_add_u64 v[2:3], v[246:247], 0, s[20:21]
	s_addc_u32 s45, s1, 0
	s_add_i32 s5, s10, s55
	global_load_lds_dwordx4 v[2:3], off
	s_mov_b32 m0, s5
	v_lshl_add_u64 v[2:3], v[248:249], 0, s[20:21]
	global_load_lds_dwordx4 v136, s[44:45]
	s_add_i32 m0, s5, 0x2000
	s_nop 0
	global_load_lds_dwordx4 v140, s[44:45]
	s_mov_b32 m0, s64
	s_nop 0
	global_load_lds_dwordx4 v[2:3], off
	v_lshl_add_u64 v[2:3], v[250:251], 0, s[20:21]
	s_mov_b32 m0, s65
	s_nop 0
	global_load_lds_dwordx4 v[2:3], off
	s_waitcnt vmcnt(8)
	s_waitcnt lgkmcnt(0)
	s_barrier
	s_setprio 1
	s_waitcnt lgkmcnt(0)
	v_mfma_f32_16x16x32_bf16 v[2:5], v[18:21], v[34:37], v[130:133]
	v_mfma_f32_16x16x32_bf16 v[62:65], v[22:25], v[38:41], v[2:5]
	v_mfma_f32_16x16x32_bf16 v[2:5], v[30:33], v[34:37], v[146:149]
	v_mfma_f32_16x16x32_bf16 v[58:61], v[200:203], v[38:41], v[2:5]
	v_mfma_f32_16x16x32_bf16 v[2:5], v[18:21], v[220:223], v[150:153]
	v_mfma_f32_16x16x32_bf16 v[46:49], v[22:25], v[224:227], v[2:5]
	v_mfma_f32_16x16x32_bf16 v[2:5], v[30:33], v[220:223], v[154:157]
	v_mfma_f32_16x16x32_bf16 v[42:45], v[200:203], v[224:227], v[2:5]
	v_mfma_f32_16x16x32_bf16 v[2:5], v[18:21], v[228:231], v[164:167]
	v_mfma_f32_16x16x32_bf16 v[6:9], v[22:25], v[232:235], v[2:5]
	v_mfma_f32_16x16x32_bf16 v[2:5], v[30:33], v[228:231], v[168:171]
	v_mfma_f32_16x16x32_bf16 v[18:21], v[18:21], v[236:239], v[172:175]
	v_mfma_f32_16x16x32_bf16 v[10:13], v[30:33], v[236:239], v[10:13]
	v_mfma_f32_16x16x32_bf16 v[2:5], v[200:203], v[232:235], v[2:5]
	v_mfma_f32_16x16x32_bf16 v[22:25], v[22:25], v[240:243], v[18:21]
	v_mfma_f32_16x16x32_bf16 v[18:21], v[200:203], v[240:243], v[10:13]
	s_setprio 0
	s_setprio 1
	v_mfma_f32_16x16x32_bf16 v[10:13], v[204:207], v[34:37], v[14:17]
	v_mfma_f32_16x16x32_bf16 v[54:57], v[208:211], v[38:41], v[10:13]
	v_mfma_f32_16x16x32_bf16 v[10:13], v[212:215], v[34:37], v[176:179]
	v_mfma_f32_16x16x32_bf16 v[50:53], v[216:219], v[38:41], v[10:13]
	v_mfma_f32_16x16x32_bf16 v[10:13], v[204:207], v[220:223], v[180:183]
	v_mfma_f32_16x16x32_bf16 v[38:41], v[208:211], v[224:227], v[10:13]
	v_mfma_f32_16x16x32_bf16 v[10:13], v[212:215], v[220:223], v[184:187]
	v_mfma_f32_16x16x32_bf16 v[34:37], v[216:219], v[224:227], v[10:13]
	v_mfma_f32_16x16x32_bf16 v[10:13], v[204:207], v[228:231], v[188:191]
	v_mfma_f32_16x16x32_bf16 v[14:17], v[208:211], v[232:235], v[10:13]
	v_mfma_f32_16x16x32_bf16 v[10:13], v[212:215], v[228:231], v[192:195]
	v_mfma_f32_16x16x32_bf16 v[30:33], v[204:207], v[236:239], v[196:199]
	v_mfma_f32_16x16x32_bf16 v[26:29], v[212:215], v[236:239], v[26:29]
	v_mfma_f32_16x16x32_bf16 v[10:13], v[216:219], v[232:235], v[10:13]
	v_mfma_f32_16x16x32_bf16 v[30:33], v[208:211], v[240:243], v[30:33]
	v_mfma_f32_16x16x32_bf16 v[26:29], v[216:219], v[240:243], v[26:29]
	s_setprio 0
	s_barrier
	s_mov_b32 s10, 2
	s_cbranch_execnz .LBB0_688

.LBB0_689:
	ds_read_b128 v[146:149], v160
	ds_read_b128 v[150:153], v160 offset:1024
	ds_read_b128 v[154:157], v160 offset:2048
	ds_read_b128 v[164:167], v160 offset:3072
	ds_read_b128 v[168:171], v161
	ds_read_b128 v[172:175], v161 offset:1024
	ds_read_b128 v[176:179], v161 offset:2048
	ds_read_b128 v[180:183], v161 offset:3072
	s_add_u32 s48, s81, s10
	s_addc_u32 s49, s82, 0
	s_add_u32 s85, s83, s10
	s_addc_u32 s86, s84, 0
	s_cmp_eq_u32 s10, s0
	s_cselect_b32 s51, s5, s49
	s_cselect_b32 s50, s43, s48
	s_cselect_b32 s49, s41, s86
	s_cselect_b32 s48, s79, s85
	s_add_i32 s86, s56, 0xc000
	v_lshl_add_u64 v[216:217], v[130:131], 0, s[10:11]
	s_mov_b32 m0, s86
	s_add_i32 s85, s56, 0xe000
	ds_read_b128 v[184:187], v162
	ds_read_b128 v[188:191], v162 offset:1024
	ds_read_b128 v[192:195], v162 offset:2048
	ds_read_b128 v[196:199], v162 offset:3072
	ds_read_b128 v[200:203], v162 offset:4096
	ds_read_b128 v[204:207], v162 offset:5120
	ds_read_b128 v[208:211], v162 offset:6144
	ds_read_b128 v[212:215], v162 offset:7168
	global_load_lds_dwordx4 v[216:217], off
	v_lshl_add_u64 v[216:217], v[132:133], 0, s[10:11]
	s_mov_b32 m0, s85
	s_nop 0
	global_load_lds_dwordx4 v[216:217], off
	s_waitcnt vmcnt(8)
	s_waitcnt lgkmcnt(0)
	s_barrier
	s_setprio 1
	s_waitcnt lgkmcnt(0)
	v_mfma_f32_16x16x32_bf16 v[126:129], v[146:149], v[184:187], v[126:129]
	v_mfma_f32_16x16x32_bf16 v[122:125], v[154:157], v[184:187], v[122:125]
	v_mfma_f32_16x16x32_bf16 v[110:113], v[146:149], v[192:195], v[110:113]
	v_mfma_f32_16x16x32_bf16 v[106:109], v[154:157], v[192:195], v[106:109]
	v_mfma_f32_16x16x32_bf16 v[94:97], v[146:149], v[200:203], v[94:97]
	v_mfma_f32_16x16x32_bf16 v[90:93], v[154:157], v[200:203], v[90:93]
	v_mfma_f32_16x16x32_bf16 v[78:81], v[146:149], v[208:211], v[78:81]
	v_mfma_f32_16x16x32_bf16 v[74:77], v[154:157], v[208:211], v[74:77]
	v_mfma_f32_16x16x32_bf16 v[126:129], v[150:153], v[188:191], v[126:129]
	v_mfma_f32_16x16x32_bf16 v[122:125], v[164:167], v[188:191], v[122:125]
	v_mfma_f32_16x16x32_bf16 v[110:113], v[150:153], v[196:199], v[110:113]
	v_mfma_f32_16x16x32_bf16 v[106:109], v[164:167], v[196:199], v[106:109]
	v_mfma_f32_16x16x32_bf16 v[94:97], v[150:153], v[204:207], v[94:97]
	v_mfma_f32_16x16x32_bf16 v[90:93], v[164:167], v[204:207], v[90:93]
	v_mfma_f32_16x16x32_bf16 v[78:81], v[150:153], v[212:215], v[78:81]
	v_mfma_f32_16x16x32_bf16 v[74:77], v[164:167], v[212:215], v[74:77]
	s_setprio 0
	s_setprio 1
	v_mfma_f32_16x16x32_bf16 v[118:121], v[168:171], v[184:187], v[118:121]
	v_mfma_f32_16x16x32_bf16 v[114:117], v[176:179], v[184:187], v[114:117]
	v_mfma_f32_16x16x32_bf16 v[102:105], v[168:171], v[192:195], v[102:105]
	v_mfma_f32_16x16x32_bf16 v[98:101], v[176:179], v[192:195], v[98:101]
	v_mfma_f32_16x16x32_bf16 v[86:89], v[168:171], v[200:203], v[86:89]
	v_mfma_f32_16x16x32_bf16 v[82:85], v[176:179], v[200:203], v[82:85]
	v_mfma_f32_16x16x32_bf16 v[70:73], v[168:171], v[208:211], v[70:73]
	v_mfma_f32_16x16x32_bf16 v[66:69], v[176:179], v[208:211], v[66:69]
	v_mfma_f32_16x16x32_bf16 v[118:121], v[172:175], v[188:191], v[118:121]
	v_mfma_f32_16x16x32_bf16 v[114:117], v[180:183], v[188:191], v[114:117]
	v_mfma_f32_16x16x32_bf16 v[102:105], v[172:175], v[196:199], v[102:105]
	v_mfma_f32_16x16x32_bf16 v[98:101], v[180:183], v[196:199], v[98:101]
	v_mfma_f32_16x16x32_bf16 v[86:89], v[172:175], v[204:207], v[86:89]
	v_mfma_f32_16x16x32_bf16 v[82:85], v[180:183], v[204:207], v[82:85]
	v_mfma_f32_16x16x32_bf16 v[70:73], v[172:175], v[212:215], v[70:73]
	v_mfma_f32_16x16x32_bf16 v[66:69], v[180:183], v[212:215], v[66:69]
	s_setprio 0
	s_barrier
	s_add_i32 s87, s69, s55
	v_lshl_add_u64 v[216:217], s[48:49], 0, v[136:137]
	s_mov_b32 m0, s87
	ds_read_b128 v[184:187], v162 offset:16384
	ds_read_b128 v[188:191], v162 offset:17408
	ds_read_b128 v[192:195], v162 offset:18432
	ds_read_b128 v[196:199], v162 offset:19456
	ds_read_b128 v[200:203], v162 offset:20480
	ds_read_b128 v[204:207], v162 offset:21504
	ds_read_b128 v[208:211], v162 offset:22528
	ds_read_b128 v[212:215], v162 offset:23552
	global_load_lds_dwordx4 v[216:217], off
	s_add_i32 m0, s87, 0x2000
	s_add_u32 s88, s48, 0x40000
	v_lshl_add_u64 v[218:219], s[48:49], 0, v[140:141]
	s_addc_u32 s89, s49, 0
	s_add_i32 s87, s70, s55
	global_load_lds_dwordx4 v[218:219], off
	v_lshl_add_u64 v[220:221], s[88:89], 0, v[136:137]
	s_mov_b32 m0, s87
	v_lshl_add_u64 v[222:223], s[50:51], 0, v[138:139]
	global_load_lds_dwordx4 v[220:221], off
	v_lshl_add_u64 v[220:221], s[88:89], 0, v[140:141]
	s_add_i32 m0, s87, 0x2000
	s_nop 0
	global_load_lds_dwordx4 v[220:221], off
	v_lshl_add_u64 v[220:221], s[50:51], 0, v[134:135]
	s_mov_b32 m0, s56
	s_nop 0
	global_load_lds_dwordx4 v[220:221], off
	s_mov_b32 m0, s57
	s_nop 0
	global_load_lds_dwordx4 v[222:223], off
	s_waitcnt vmcnt(8)
	s_waitcnt lgkmcnt(0)
	s_barrier
	s_setprio 1
	s_waitcnt lgkmcnt(0)
	s_nop 0
	v_mfma_f32_16x16x32_bf16 v[62:65], v[146:149], v[184:187], v[62:65]
	v_mfma_f32_16x16x32_bf16 v[58:61], v[154:157], v[184:187], v[58:61]
	v_mfma_f32_16x16x32_bf16 v[46:49], v[146:149], v[192:195], v[46:49]
	v_mfma_f32_16x16x32_bf16 v[42:45], v[154:157], v[192:195], v[42:45]
	v_mfma_f32_16x16x32_bf16 v[6:9], v[146:149], v[200:203], v[6:9]
	v_mfma_f32_16x16x32_bf16 v[2:5], v[154:157], v[200:203], v[2:5]
	v_mfma_f32_16x16x32_bf16 v[22:25], v[146:149], v[208:211], v[22:25]
	v_mfma_f32_16x16x32_bf16 v[18:21], v[154:157], v[208:211], v[18:21]
	v_mfma_f32_16x16x32_bf16 v[62:65], v[150:153], v[188:191], v[62:65]
	v_mfma_f32_16x16x32_bf16 v[58:61], v[164:167], v[188:191], v[58:61]
	v_mfma_f32_16x16x32_bf16 v[46:49], v[150:153], v[196:199], v[46:49]
	v_mfma_f32_16x16x32_bf16 v[42:45], v[164:167], v[196:199], v[42:45]
	v_mfma_f32_16x16x32_bf16 v[6:9], v[150:153], v[204:207], v[6:9]
	v_mfma_f32_16x16x32_bf16 v[2:5], v[164:167], v[204:207], v[2:5]
	v_mfma_f32_16x16x32_bf16 v[22:25], v[150:153], v[212:215], v[22:25]
	v_mfma_f32_16x16x32_bf16 v[18:21], v[164:167], v[212:215], v[18:21]
	s_setprio 0
	s_setprio 1
	v_mfma_f32_16x16x32_bf16 v[54:57], v[168:171], v[184:187], v[54:57]
	v_mfma_f32_16x16x32_bf16 v[50:53], v[176:179], v[184:187], v[50:53]
	v_mfma_f32_16x16x32_bf16 v[38:41], v[168:171], v[192:195], v[38:41]
	v_mfma_f32_16x16x32_bf16 v[34:37], v[176:179], v[192:195], v[34:37]
	v_mfma_f32_16x16x32_bf16 v[14:17], v[168:171], v[200:203], v[14:17]
	v_mfma_f32_16x16x32_bf16 v[10:13], v[176:179], v[200:203], v[10:13]
	v_mfma_f32_16x16x32_bf16 v[30:33], v[168:171], v[208:211], v[30:33]
	v_mfma_f32_16x16x32_bf16 v[26:29], v[176:179], v[208:211], v[26:29]
	v_mfma_f32_16x16x32_bf16 v[54:57], v[172:175], v[188:191], v[54:57]
	v_mfma_f32_16x16x32_bf16 v[50:53], v[180:183], v[188:191], v[50:53]
	v_mfma_f32_16x16x32_bf16 v[38:41], v[172:175], v[196:199], v[38:41]
	v_mfma_f32_16x16x32_bf16 v[34:37], v[180:183], v[196:199], v[34:37]
	v_mfma_f32_16x16x32_bf16 v[14:17], v[172:175], v[204:207], v[14:17]
	v_mfma_f32_16x16x32_bf16 v[10:13], v[180:183], v[204:207], v[10:13]
	v_mfma_f32_16x16x32_bf16 v[30:33], v[172:175], v[212:215], v[30:33]
	v_mfma_f32_16x16x32_bf16 v[26:29], v[180:183], v[212:215], v[26:29]
	s_setprio 0
	s_barrier
	s_add_i32 s87, 0, 0x18000
	v_add_u32_e32 v163, s87, v159
	s_add_i32 s88, 0, 0x1c000
	ds_read_b128 v[146:149], v163
	ds_read_b128 v[150:153], v163 offset:1024
	ds_read_b128 v[154:157], v163 offset:2048
	ds_read_b128 v[164:167], v163 offset:3072
	v_add_u32_e32 v163, s88, v159
	ds_read_b128 v[168:171], v163
	ds_read_b128 v[172:175], v163 offset:1024
	ds_read_b128 v[176:179], v163 offset:2048
	ds_read_b128 v[180:183], v163 offset:3072
	s_add_u32 s50, s50, 0x40000
	s_addc_u32 s51, s51, 0
	s_mov_b32 m0, s58
	v_lshl_add_u64 v[224:225], s[50:51], 0, v[134:135]
	ds_read_b128 v[184:187], v162 offset:32768
	ds_read_b128 v[188:191], v162 offset:33792
	ds_read_b128 v[192:195], v162 offset:34816
	ds_read_b128 v[196:199], v162 offset:35840
	ds_read_b128 v[200:203], v162 offset:36864
	ds_read_b128 v[204:207], v162 offset:37888
	ds_read_b128 v[208:211], v162 offset:38912
	ds_read_b128 v[212:215], v162 offset:39936
	global_load_lds_dwordx4 v[224:225], off
	v_lshl_add_u64 v[224:225], s[50:51], 0, v[138:139]
	s_mov_b32 m0, s59
	s_nop 0
	global_load_lds_dwordx4 v[224:225], off
	s_waitcnt vmcnt(8)
	s_waitcnt lgkmcnt(0)
	s_barrier
	s_setprio 1
	s_waitcnt lgkmcnt(0)
	s_nop 0
	v_mfma_f32_16x16x32_bf16 v[126:129], v[146:149], v[184:187], v[126:129]
	v_mfma_f32_16x16x32_bf16 v[122:125], v[154:157], v[184:187], v[122:125]
	v_mfma_f32_16x16x32_bf16 v[110:113], v[146:149], v[192:195], v[110:113]
	v_mfma_f32_16x16x32_bf16 v[106:109], v[154:157], v[192:195], v[106:109]
	v_mfma_f32_16x16x32_bf16 v[94:97], v[146:149], v[200:203], v[94:97]
	v_mfma_f32_16x16x32_bf16 v[90:93], v[154:157], v[200:203], v[90:93]
	v_mfma_f32_16x16x32_bf16 v[78:81], v[146:149], v[208:211], v[78:81]
	v_mfma_f32_16x16x32_bf16 v[74:77], v[154:157], v[208:211], v[74:77]
	v_mfma_f32_16x16x32_bf16 v[126:129], v[150:153], v[188:191], v[126:129]
	v_mfma_f32_16x16x32_bf16 v[122:125], v[164:167], v[188:191], v[122:125]
	v_mfma_f32_16x16x32_bf16 v[110:113], v[150:153], v[196:199], v[110:113]
	v_mfma_f32_16x16x32_bf16 v[106:109], v[164:167], v[196:199], v[106:109]
	v_mfma_f32_16x16x32_bf16 v[94:97], v[150:153], v[204:207], v[94:97]
	v_mfma_f32_16x16x32_bf16 v[90:93], v[164:167], v[204:207], v[90:93]
	v_mfma_f32_16x16x32_bf16 v[78:81], v[150:153], v[212:215], v[78:81]
	v_mfma_f32_16x16x32_bf16 v[74:77], v[164:167], v[212:215], v[74:77]
	s_setprio 0
	s_setprio 1
	v_mfma_f32_16x16x32_bf16 v[118:121], v[168:171], v[184:187], v[118:121]
	v_mfma_f32_16x16x32_bf16 v[114:117], v[176:179], v[184:187], v[114:117]
	v_mfma_f32_16x16x32_bf16 v[102:105], v[168:171], v[192:195], v[102:105]
	v_mfma_f32_16x16x32_bf16 v[98:101], v[176:179], v[192:195], v[98:101]
	v_mfma_f32_16x16x32_bf16 v[86:89], v[168:171], v[200:203], v[86:89]
	v_mfma_f32_16x16x32_bf16 v[82:85], v[176:179], v[200:203], v[82:85]
	v_mfma_f32_16x16x32_bf16 v[70:73], v[168:171], v[208:211], v[70:73]
	v_mfma_f32_16x16x32_bf16 v[66:69], v[176:179], v[208:211], v[66:69]
	v_mfma_f32_16x16x32_bf16 v[118:121], v[172:175], v[188:191], v[118:121]
	v_mfma_f32_16x16x32_bf16 v[114:117], v[180:183], v[188:191], v[114:117]
	v_mfma_f32_16x16x32_bf16 v[102:105], v[172:175], v[196:199], v[102:105]
	v_mfma_f32_16x16x32_bf16 v[98:101], v[180:183], v[196:199], v[98:101]
	v_mfma_f32_16x16x32_bf16 v[86:89], v[172:175], v[204:207], v[86:89]
	v_mfma_f32_16x16x32_bf16 v[82:85], v[180:183], v[204:207], v[82:85]
	v_mfma_f32_16x16x32_bf16 v[70:73], v[172:175], v[212:215], v[70:73]
	v_mfma_f32_16x16x32_bf16 v[66:69], v[180:183], v[212:215], v[66:69]
	s_setprio 0
	s_barrier
	s_add_i32 s50, s87, s55
	v_lshl_add_u64 v[216:217], v[216:217], 0, s[14:15]
	s_mov_b32 m0, s50
	ds_read_b128 v[184:187], v162 offset:49152
	ds_read_b128 v[188:191], v162 offset:50176
	ds_read_b128 v[192:195], v162 offset:51200
	ds_read_b128 v[196:199], v162 offset:52224
	ds_read_b128 v[200:203], v162 offset:53248
	ds_read_b128 v[204:207], v162 offset:54272
	ds_read_b128 v[208:211], v162 offset:55296
	ds_read_b128 v[212:215], v162 offset:56320
	global_load_lds_dwordx4 v[216:217], off
	s_add_i32 m0, s50, 0x2000
	s_add_u32 s48, s48, 0x40080
	v_lshl_add_u64 v[216:217], v[218:219], 0, s[14:15]
	s_addc_u32 s49, s49, 0
	s_add_i32 s50, s88, s55
	global_load_lds_dwordx4 v[216:217], off
	v_lshl_add_u64 v[216:217], s[48:49], 0, v[136:137]
	s_mov_b32 m0, s50
	s_nop 0
	global_load_lds_dwordx4 v[216:217], off
	v_lshl_add_u64 v[216:217], s[48:49], 0, v[140:141]
	s_add_i32 m0, s50, 0x2000
	s_nop 0
	global_load_lds_dwordx4 v[216:217], off
	v_lshl_add_u64 v[216:217], v[220:221], 0, s[14:15]
	s_mov_b32 m0, s64
	s_nop 0
	global_load_lds_dwordx4 v[216:217], off
	v_lshl_add_u64 v[216:217], v[222:223], 0, s[14:15]
	s_mov_b32 m0, s65
	s_nop 0
	global_load_lds_dwordx4 v[216:217], off
	s_waitcnt vmcnt(8)
	s_waitcnt lgkmcnt(0)
	s_barrier
	s_setprio 1
	s_waitcnt lgkmcnt(0)
	v_mfma_f32_16x16x32_bf16 v[62:65], v[146:149], v[184:187], v[62:65]
	v_mfma_f32_16x16x32_bf16 v[58:61], v[154:157], v[184:187], v[58:61]
	v_mfma_f32_16x16x32_bf16 v[46:49], v[146:149], v[192:195], v[46:49]
	v_mfma_f32_16x16x32_bf16 v[42:45], v[154:157], v[192:195], v[42:45]
	v_mfma_f32_16x16x32_bf16 v[6:9], v[146:149], v[200:203], v[6:9]
	v_mfma_f32_16x16x32_bf16 v[2:5], v[154:157], v[200:203], v[2:5]
	v_mfma_f32_16x16x32_bf16 v[22:25], v[146:149], v[208:211], v[22:25]
	v_mfma_f32_16x16x32_bf16 v[18:21], v[154:157], v[208:211], v[18:21]
	v_mfma_f32_16x16x32_bf16 v[62:65], v[150:153], v[188:191], v[62:65]
	v_mfma_f32_16x16x32_bf16 v[58:61], v[164:167], v[188:191], v[58:61]
	v_mfma_f32_16x16x32_bf16 v[46:49], v[150:153], v[196:199], v[46:49]
	v_mfma_f32_16x16x32_bf16 v[42:45], v[164:167], v[196:199], v[42:45]
	v_mfma_f32_16x16x32_bf16 v[6:9], v[150:153], v[204:207], v[6:9]
	v_mfma_f32_16x16x32_bf16 v[2:5], v[164:167], v[204:207], v[2:5]
	v_mfma_f32_16x16x32_bf16 v[22:25], v[150:153], v[212:215], v[22:25]
	v_mfma_f32_16x16x32_bf16 v[18:21], v[164:167], v[212:215], v[18:21]
	s_setprio 0
	s_setprio 1
	v_mfma_f32_16x16x32_bf16 v[54:57], v[168:171], v[184:187], v[54:57]
	v_mfma_f32_16x16x32_bf16 v[50:53], v[176:179], v[184:187], v[50:53]
	v_mfma_f32_16x16x32_bf16 v[38:41], v[168:171], v[192:195], v[38:41]
	v_mfma_f32_16x16x32_bf16 v[34:37], v[176:179], v[192:195], v[34:37]
	v_mfma_f32_16x16x32_bf16 v[14:17], v[168:171], v[200:203], v[14:17]
	v_mfma_f32_16x16x32_bf16 v[10:13], v[176:179], v[200:203], v[10:13]
	v_mfma_f32_16x16x32_bf16 v[30:33], v[168:171], v[208:211], v[30:33]
	v_mfma_f32_16x16x32_bf16 v[26:29], v[176:179], v[208:211], v[26:29]
	v_mfma_f32_16x16x32_bf16 v[54:57], v[172:175], v[188:191], v[54:57]
	v_mfma_f32_16x16x32_bf16 v[50:53], v[180:183], v[188:191], v[50:53]
	v_mfma_f32_16x16x32_bf16 v[38:41], v[172:175], v[196:199], v[38:41]
	v_mfma_f32_16x16x32_bf16 v[34:37], v[180:183], v[196:199], v[34:37]
	v_mfma_f32_16x16x32_bf16 v[14:17], v[172:175], v[204:207], v[14:17]
	v_mfma_f32_16x16x32_bf16 v[10:13], v[180:183], v[204:207], v[10:13]
	v_mfma_f32_16x16x32_bf16 v[30:33], v[172:175], v[212:215], v[30:33]
	v_mfma_f32_16x16x32_bf16 v[26:29], v[180:183], v[212:215], v[26:29]
	s_setprio 0
	s_barrier
	s_add_i32 s80, s80, 2
	s_add_u32 s81, s81, 0x100
	s_addc_u32 s82, s82, 0
	s_add_u32 s83, s83, 0x100
	s_addc_u32 s84, s84, 0
	s_add_u32 s0, s0, 0xffffff00
	s_addc_u32 s1, s1, -1
	v_lshl_add_u64 v[130:131], v[130:131], 0, s[18:19]
	s_cmp_gt_u32 s80, 13
	v_lshl_add_u64 v[132:133], v[132:133], 0, s[18:19]
	s_cbranch_scc0 .LBB0_689
	s_add_u32 s0, s43, 0x40080
	s_addc_u32 s1, s5, 0
	s_mov_b32 m0, s86
	v_lshl_add_u64 v[130:131], s[0:1], 0, v[134:135]
	global_load_lds_dwordx4 v[130:131], off
	v_lshl_add_u64 v[130:131], s[0:1], 0, v[138:139]
	s_mov_b32 m0, s85
	s_and_b64 vcc, exec, s[16:17]
	global_load_lds_dwordx4 v[130:131], off
	s_cbranch_vccz .LBB0_692
	s_barrier

.LBB0_771:
	ds_read_b128 v[130:133], v180
	ds_read_b128 v[134:137], v180 offset:1024
	ds_read_b128 v[138:141], v180 offset:2048
	ds_read_b128 v[142:145], v180 offset:3072
	ds_read_b128 v[146:149], v181
	ds_read_b128 v[166:169], v181 offset:1024
	ds_read_b128 v[170:173], v181 offset:2048
	ds_read_b128 v[174:177], v181 offset:3072
	s_add_u32 s36, s0, 0xfffc0080
	s_addc_u32 s37, s1, -1
	s_cmp_eq_u32 s58, 12
	s_cselect_b32 s39, s27, s37
	s_cselect_b32 s38, s54, s36
	s_cselect_b32 s37, s25, s57
	s_cselect_b32 s36, s55, s56
	v_lshl_add_u64 v[216:217], s[0:1], 0, v[158:159]
	s_add_i32 m0, s35, 0xc000
	ds_read_b128 v[184:187], v182
	ds_read_b128 v[188:191], v182 offset:1024
	ds_read_b128 v[192:195], v182 offset:2048
	ds_read_b128 v[196:199], v182 offset:3072
	ds_read_b128 v[200:203], v182 offset:4096
	ds_read_b128 v[204:207], v182 offset:5120
	ds_read_b128 v[208:211], v182 offset:6144
	ds_read_b128 v[212:215], v182 offset:7168
	global_load_lds_dwordx4 v[216:217], off
	v_lshl_add_u64 v[216:217], s[0:1], 0, v[160:161]
	s_add_i32 m0, s35, 0xe000
	s_nop 0
	global_load_lds_dwordx4 v[216:217], off
	s_waitcnt vmcnt(8)
	s_waitcnt lgkmcnt(0)
	s_barrier
	s_setprio 1
	s_waitcnt lgkmcnt(0)
	s_nop 0
	v_mfma_f32_16x16x32_bf16 v[126:129], v[130:133], v[184:187], v[126:129]
	v_mfma_f32_16x16x32_bf16 v[122:125], v[138:141], v[184:187], v[122:125]
	v_mfma_f32_16x16x32_bf16 v[110:113], v[130:133], v[192:195], v[110:113]
	v_mfma_f32_16x16x32_bf16 v[106:109], v[138:141], v[192:195], v[106:109]
	v_mfma_f32_16x16x32_bf16 v[94:97], v[130:133], v[200:203], v[94:97]
	v_mfma_f32_16x16x32_bf16 v[90:93], v[138:141], v[200:203], v[90:93]
	v_mfma_f32_16x16x32_bf16 v[78:81], v[130:133], v[208:211], v[78:81]
	v_mfma_f32_16x16x32_bf16 v[74:77], v[138:141], v[208:211], v[74:77]
	v_mfma_f32_16x16x32_bf16 v[126:129], v[134:137], v[188:191], v[126:129]
	v_mfma_f32_16x16x32_bf16 v[122:125], v[142:145], v[188:191], v[122:125]
	v_mfma_f32_16x16x32_bf16 v[110:113], v[134:137], v[196:199], v[110:113]
	v_mfma_f32_16x16x32_bf16 v[106:109], v[142:145], v[196:199], v[106:109]
	v_mfma_f32_16x16x32_bf16 v[94:97], v[134:137], v[204:207], v[94:97]
	v_mfma_f32_16x16x32_bf16 v[90:93], v[142:145], v[204:207], v[90:93]
	v_mfma_f32_16x16x32_bf16 v[78:81], v[134:137], v[212:215], v[78:81]
	v_mfma_f32_16x16x32_bf16 v[74:77], v[142:145], v[212:215], v[74:77]
	s_setprio 0
	s_setprio 1
	v_mfma_f32_16x16x32_bf16 v[118:121], v[146:149], v[184:187], v[118:121]
	v_mfma_f32_16x16x32_bf16 v[114:117], v[170:173], v[184:187], v[114:117]
	v_mfma_f32_16x16x32_bf16 v[102:105], v[146:149], v[192:195], v[102:105]
	v_mfma_f32_16x16x32_bf16 v[98:101], v[170:173], v[192:195], v[98:101]
	v_mfma_f32_16x16x32_bf16 v[86:89], v[146:149], v[200:203], v[86:89]
	v_mfma_f32_16x16x32_bf16 v[82:85], v[170:173], v[200:203], v[82:85]
	v_mfma_f32_16x16x32_bf16 v[70:73], v[146:149], v[208:211], v[70:73]
	v_mfma_f32_16x16x32_bf16 v[66:69], v[170:173], v[208:211], v[66:69]
	v_mfma_f32_16x16x32_bf16 v[118:121], v[166:169], v[188:191], v[118:121]
	v_mfma_f32_16x16x32_bf16 v[114:117], v[174:177], v[188:191], v[114:117]
	v_mfma_f32_16x16x32_bf16 v[102:105], v[166:169], v[196:199], v[102:105]
	v_mfma_f32_16x16x32_bf16 v[98:101], v[174:177], v[196:199], v[98:101]
	v_mfma_f32_16x16x32_bf16 v[86:89], v[166:169], v[204:207], v[86:89]
	v_mfma_f32_16x16x32_bf16 v[82:85], v[174:177], v[204:207], v[82:85]
	v_mfma_f32_16x16x32_bf16 v[70:73], v[166:169], v[212:215], v[70:73]
	v_mfma_f32_16x16x32_bf16 v[66:69], v[174:177], v[212:215], v[66:69]
	s_setprio 0
	s_barrier
	s_add_i32 s59, s51, s43
	v_lshl_add_u64 v[216:217], s[36:37], 0, v[152:153]
	s_mov_b32 m0, s59
	ds_read_b128 v[184:187], v182 offset:16384
	ds_read_b128 v[188:191], v182 offset:17408
	ds_read_b128 v[192:195], v182 offset:18432
	ds_read_b128 v[196:199], v182 offset:19456
	ds_read_b128 v[200:203], v182 offset:20480
	ds_read_b128 v[204:207], v182 offset:21504
	ds_read_b128 v[208:211], v182 offset:22528
	ds_read_b128 v[212:215], v182 offset:23552
	global_load_lds_dwordx4 v[216:217], off
	s_add_i32 m0, s59, 0x2000
	s_add_u32 s60, s36, 0x40000
	v_lshl_add_u64 v[218:219], s[36:37], 0, v[156:157]
	s_addc_u32 s61, s37, 0
	s_add_i32 s59, s52, s43
	global_load_lds_dwordx4 v[218:219], off
	v_lshl_add_u64 v[220:221], s[60:61], 0, v[152:153]
	s_mov_b32 m0, s59
	v_lshl_add_u64 v[222:223], s[38:39], 0, v[154:155]
	global_load_lds_dwordx4 v[220:221], off
	v_lshl_add_u64 v[220:221], s[60:61], 0, v[156:157]
	s_add_i32 m0, s59, 0x2000
	s_nop 0
	global_load_lds_dwordx4 v[220:221], off
	v_lshl_add_u64 v[220:221], s[38:39], 0, v[150:151]
	s_mov_b32 m0, s35
	s_nop 0
	global_load_lds_dwordx4 v[220:221], off
	s_mov_b32 m0, s44
	s_nop 0
	global_load_lds_dwordx4 v[222:223], off
	s_waitcnt vmcnt(8)
	s_waitcnt lgkmcnt(0)
	s_barrier
	s_setprio 1
	s_waitcnt lgkmcnt(0)
	s_nop 0
	v_mfma_f32_16x16x32_bf16 v[6:9], v[130:133], v[184:187], v[6:9]
	v_mfma_f32_16x16x32_bf16 v[2:5], v[138:141], v[184:187], v[2:5]
	v_mfma_f32_16x16x32_bf16 v[22:25], v[130:133], v[192:195], v[22:25]
	v_mfma_f32_16x16x32_bf16 v[18:21], v[138:141], v[192:195], v[18:21]
	v_mfma_f32_16x16x32_bf16 v[38:41], v[130:133], v[200:203], v[38:41]
	v_mfma_f32_16x16x32_bf16 v[34:37], v[138:141], v[200:203], v[34:37]
	v_mfma_f32_16x16x32_bf16 v[54:57], v[130:133], v[208:211], v[54:57]
	v_mfma_f32_16x16x32_bf16 v[50:53], v[138:141], v[208:211], v[50:53]
	v_mfma_f32_16x16x32_bf16 v[6:9], v[134:137], v[188:191], v[6:9]
	v_mfma_f32_16x16x32_bf16 v[2:5], v[142:145], v[188:191], v[2:5]
	v_mfma_f32_16x16x32_bf16 v[22:25], v[134:137], v[196:199], v[22:25]
	v_mfma_f32_16x16x32_bf16 v[18:21], v[142:145], v[196:199], v[18:21]
	v_mfma_f32_16x16x32_bf16 v[38:41], v[134:137], v[204:207], v[38:41]
	v_mfma_f32_16x16x32_bf16 v[34:37], v[142:145], v[204:207], v[34:37]
	v_mfma_f32_16x16x32_bf16 v[54:57], v[134:137], v[212:215], v[54:57]
	v_mfma_f32_16x16x32_bf16 v[50:53], v[142:145], v[212:215], v[50:53]
	s_setprio 0
	s_setprio 1
	v_mfma_f32_16x16x32_bf16 v[14:17], v[146:149], v[184:187], v[14:17]
	v_mfma_f32_16x16x32_bf16 v[10:13], v[170:173], v[184:187], v[10:13]
	v_mfma_f32_16x16x32_bf16 v[30:33], v[146:149], v[192:195], v[30:33]
	v_mfma_f32_16x16x32_bf16 v[26:29], v[170:173], v[192:195], v[26:29]
	v_mfma_f32_16x16x32_bf16 v[46:49], v[146:149], v[200:203], v[46:49]
	v_mfma_f32_16x16x32_bf16 v[42:45], v[170:173], v[200:203], v[42:45]
	v_mfma_f32_16x16x32_bf16 v[62:65], v[146:149], v[208:211], v[62:65]
	v_mfma_f32_16x16x32_bf16 v[58:61], v[170:173], v[208:211], v[58:61]
	v_mfma_f32_16x16x32_bf16 v[14:17], v[166:169], v[188:191], v[14:17]
	v_mfma_f32_16x16x32_bf16 v[10:13], v[174:177], v[188:191], v[10:13]
	v_mfma_f32_16x16x32_bf16 v[30:33], v[166:169], v[196:199], v[30:33]
	v_mfma_f32_16x16x32_bf16 v[26:29], v[174:177], v[196:199], v[26:29]
	v_mfma_f32_16x16x32_bf16 v[46:49], v[166:169], v[204:207], v[46:49]
	v_mfma_f32_16x16x32_bf16 v[42:45], v[174:177], v[204:207], v[42:45]
	v_mfma_f32_16x16x32_bf16 v[62:65], v[166:169], v[212:215], v[62:65]
	v_mfma_f32_16x16x32_bf16 v[58:61], v[174:177], v[212:215], v[58:61]
	s_setprio 0
	s_barrier
	s_cmp_lg_u32 s58, 12
	s_cbranch_scc1 .Lmy_p5_nox
	v_lshl_or_b32 v183, s53, 8, v179
	v_lshl_add_u32 v226, s34, 8, v1
	v_lshlrev_b32_e32 v183, 1, v183
	v_lshl_add_u32 v183, v226, 11, v183
	global_load_dwordx4 v[226:229], v183, s[12:13]
	global_load_dwordx4 v[230:233], v183, s[12:13] offset:256
	v_add_u32_e32 v183, 0x8000, v183
	global_load_dwordx4 v[234:237], v183, s[12:13]
	global_load_dwordx4 v[238:241], v183, s[12:13] offset:256
	v_add_u32_e32 v183, 0x8000, v183
	global_load_dwordx4 v[242:245], v183, s[12:13]
	global_load_dwordx4 v[246:249], v183, s[12:13] offset:256
	v_add_u32_e32 v183, 0x8000, v183
	global_load_dwordx4 v[250:253], v183, s[12:13]
	global_load_dwordx4 v[162:165], v183, s[12:13] offset:256

.LBB0_796:
	ds_read_b128 v[130:133], v162
	ds_read_b128 v[134:137], v162 offset:1024
	ds_read_b128 v[154:157], v162 offset:2048
	ds_read_b128 v[166:169], v162 offset:3072
	ds_read_b128 v[170:173], v163
	ds_read_b128 v[174:177], v163 offset:1024
	ds_read_b128 v[178:181], v163 offset:2048
	ds_read_b128 v[182:185], v163 offset:3072
	s_add_u32 s28, s0, 0xfff80080
	s_addc_u32 s29, s1, -1
	s_cmp_eq_u32 s54, 28
	s_cselect_b32 s31, s21, s29
	s_cselect_b32 s30, s50, s28
	s_cselect_b32 s29, s19, s53
	s_cselect_b32 s28, s51, s52
	v_lshl_add_u64 v[158:159], s[0:1], 0, v[146:147]
	s_add_i32 m0, s27, 0xc000
	ds_read_b128 v[186:189], v164
	ds_read_b128 v[190:193], v164 offset:1024
	ds_read_b128 v[194:197], v164 offset:2048
	ds_read_b128 v[198:201], v164 offset:3072
	ds_read_b128 v[202:205], v164 offset:4096
	ds_read_b128 v[206:209], v164 offset:5120
	ds_read_b128 v[210:213], v164 offset:6144
	ds_read_b128 v[214:217], v164 offset:7168
	global_load_lds_dwordx4 v[158:159], off
	v_lshl_add_u64 v[158:159], s[0:1], 0, v[148:149]
	s_add_i32 m0, s27, 0xe000
	s_nop 0
	global_load_lds_dwordx4 v[158:159], off
	s_waitcnt vmcnt(8)
	s_waitcnt lgkmcnt(0)
	s_barrier
	s_setprio 1
	s_waitcnt lgkmcnt(0)
	v_mfma_f32_16x16x32_bf16 v[126:129], v[130:133], v[186:189], v[126:129]
	v_mfma_f32_16x16x32_bf16 v[122:125], v[154:157], v[186:189], v[122:125]
	v_mfma_f32_16x16x32_bf16 v[110:113], v[130:133], v[194:197], v[110:113]
	v_mfma_f32_16x16x32_bf16 v[106:109], v[154:157], v[194:197], v[106:109]
	v_mfma_f32_16x16x32_bf16 v[94:97], v[130:133], v[202:205], v[94:97]
	v_mfma_f32_16x16x32_bf16 v[90:93], v[154:157], v[202:205], v[90:93]
	v_mfma_f32_16x16x32_bf16 v[78:81], v[130:133], v[210:213], v[78:81]
	v_mfma_f32_16x16x32_bf16 v[74:77], v[154:157], v[210:213], v[74:77]
	v_mfma_f32_16x16x32_bf16 v[126:129], v[134:137], v[190:193], v[126:129]
	v_mfma_f32_16x16x32_bf16 v[122:125], v[166:169], v[190:193], v[122:125]
	v_mfma_f32_16x16x32_bf16 v[110:113], v[134:137], v[198:201], v[110:113]
	v_mfma_f32_16x16x32_bf16 v[106:109], v[166:169], v[198:201], v[106:109]
	v_mfma_f32_16x16x32_bf16 v[94:97], v[134:137], v[206:209], v[94:97]
	v_mfma_f32_16x16x32_bf16 v[90:93], v[166:169], v[206:209], v[90:93]
	v_mfma_f32_16x16x32_bf16 v[78:81], v[134:137], v[214:217], v[78:81]
	v_mfma_f32_16x16x32_bf16 v[74:77], v[166:169], v[214:217], v[74:77]
	s_setprio 0
	s_setprio 1
	v_mfma_f32_16x16x32_bf16 v[118:121], v[170:173], v[186:189], v[118:121]
	v_mfma_f32_16x16x32_bf16 v[114:117], v[178:181], v[186:189], v[114:117]
	v_mfma_f32_16x16x32_bf16 v[102:105], v[170:173], v[194:197], v[102:105]
	v_mfma_f32_16x16x32_bf16 v[98:101], v[178:181], v[194:197], v[98:101]
	v_mfma_f32_16x16x32_bf16 v[86:89], v[170:173], v[202:205], v[86:89]
	v_mfma_f32_16x16x32_bf16 v[82:85], v[178:181], v[202:205], v[82:85]
	v_mfma_f32_16x16x32_bf16 v[70:73], v[170:173], v[210:213], v[70:73]
	v_mfma_f32_16x16x32_bf16 v[66:69], v[178:181], v[210:213], v[66:69]
	v_mfma_f32_16x16x32_bf16 v[118:121], v[174:177], v[190:193], v[118:121]
	v_mfma_f32_16x16x32_bf16 v[114:117], v[182:185], v[190:193], v[114:117]
	v_mfma_f32_16x16x32_bf16 v[102:105], v[174:177], v[198:201], v[102:105]
	v_mfma_f32_16x16x32_bf16 v[98:101], v[182:185], v[198:201], v[98:101]
	v_mfma_f32_16x16x32_bf16 v[86:89], v[174:177], v[206:209], v[86:89]
	v_mfma_f32_16x16x32_bf16 v[82:85], v[182:185], v[206:209], v[82:85]
	v_mfma_f32_16x16x32_bf16 v[70:73], v[174:177], v[214:217], v[70:73]
	v_mfma_f32_16x16x32_bf16 v[66:69], v[182:185], v[214:217], v[66:69]
	s_setprio 0
	s_barrier
	s_add_i32 s55, s47, s39
	v_lshl_add_u64 v[158:159], s[28:29], 0, v[140:141]
	s_mov_b32 m0, s55
	ds_read_b128 v[186:189], v164 offset:16384
	ds_read_b128 v[190:193], v164 offset:17408
	ds_read_b128 v[194:197], v164 offset:18432
	ds_read_b128 v[198:201], v164 offset:19456
	ds_read_b128 v[202:205], v164 offset:20480
	ds_read_b128 v[206:209], v164 offset:21504
	ds_read_b128 v[210:213], v164 offset:22528
	ds_read_b128 v[214:217], v164 offset:23552
	global_load_lds_dwordx4 v[158:159], off
	s_add_i32 m0, s55, 0x2000
	s_add_u32 s56, s28, 0x80000
	v_lshl_add_u64 v[218:219], s[28:29], 0, v[144:145]
	s_addc_u32 s57, s29, 0
	s_add_i32 s55, s48, s39
	global_load_lds_dwordx4 v[218:219], off
	v_lshl_add_u64 v[220:221], s[56:57], 0, v[140:141]
	s_mov_b32 m0, s55
	v_lshl_add_u64 v[222:223], s[30:31], 0, v[142:143]
	global_load_lds_dwordx4 v[220:221], off
	v_lshl_add_u64 v[220:221], s[56:57], 0, v[144:145]
	s_add_i32 m0, s55, 0x2000
	s_nop 0
	global_load_lds_dwordx4 v[220:221], off
	v_lshl_add_u64 v[220:221], s[30:31], 0, v[138:139]
	s_mov_b32 m0, s27
	s_nop 0
	global_load_lds_dwordx4 v[220:221], off
	s_mov_b32 m0, s40
	s_nop 0
	global_load_lds_dwordx4 v[222:223], off
	s_waitcnt vmcnt(8)
	s_waitcnt lgkmcnt(0)
	s_barrier
	s_setprio 1
	s_waitcnt lgkmcnt(0)
	s_nop 0
	v_mfma_f32_16x16x32_bf16 v[62:65], v[130:133], v[186:189], v[62:65]
	v_mfma_f32_16x16x32_bf16 v[58:61], v[154:157], v[186:189], v[58:61]
	v_mfma_f32_16x16x32_bf16 v[46:49], v[130:133], v[194:197], v[46:49]
	v_mfma_f32_16x16x32_bf16 v[42:45], v[154:157], v[194:197], v[42:45]
	v_mfma_f32_16x16x32_bf16 v[6:9], v[130:133], v[202:205], v[6:9]
	v_mfma_f32_16x16x32_bf16 v[2:5], v[154:157], v[202:205], v[2:5]
	v_mfma_f32_16x16x32_bf16 v[22:25], v[130:133], v[210:213], v[22:25]
	v_mfma_f32_16x16x32_bf16 v[18:21], v[154:157], v[210:213], v[18:21]
	v_mfma_f32_16x16x32_bf16 v[62:65], v[134:137], v[190:193], v[62:65]
	v_mfma_f32_16x16x32_bf16 v[58:61], v[166:169], v[190:193], v[58:61]
	v_mfma_f32_16x16x32_bf16 v[46:49], v[134:137], v[198:201], v[46:49]
	v_mfma_f32_16x16x32_bf16 v[42:45], v[166:169], v[198:201], v[42:45]
	v_mfma_f32_16x16x32_bf16 v[6:9], v[134:137], v[206:209], v[6:9]
	v_mfma_f32_16x16x32_bf16 v[2:5], v[166:169], v[206:209], v[2:5]
	v_mfma_f32_16x16x32_bf16 v[22:25], v[134:137], v[214:217], v[22:25]
	v_mfma_f32_16x16x32_bf16 v[18:21], v[166:169], v[214:217], v[18:21]
	s_setprio 0
	s_setprio 1
	v_mfma_f32_16x16x32_bf16 v[54:57], v[170:173], v[186:189], v[54:57]
	v_mfma_f32_16x16x32_bf16 v[50:53], v[178:181], v[186:189], v[50:53]
	v_mfma_f32_16x16x32_bf16 v[38:41], v[170:173], v[194:197], v[38:41]
	v_mfma_f32_16x16x32_bf16 v[34:37], v[178:181], v[194:197], v[34:37]
	v_mfma_f32_16x16x32_bf16 v[14:17], v[170:173], v[202:205], v[14:17]
	v_mfma_f32_16x16x32_bf16 v[10:13], v[178:181], v[202:205], v[10:13]
	v_mfma_f32_16x16x32_bf16 v[30:33], v[170:173], v[210:213], v[30:33]
	v_mfma_f32_16x16x32_bf16 v[26:29], v[178:181], v[210:213], v[26:29]
	v_mfma_f32_16x16x32_bf16 v[54:57], v[174:177], v[190:193], v[54:57]
	v_mfma_f32_16x16x32_bf16 v[50:53], v[182:185], v[190:193], v[50:53]
	v_mfma_f32_16x16x32_bf16 v[38:41], v[174:177], v[198:201], v[38:41]
	v_mfma_f32_16x16x32_bf16 v[34:37], v[182:185], v[198:201], v[34:37]
	v_mfma_f32_16x16x32_bf16 v[14:17], v[174:177], v[206:209], v[14:17]
	v_mfma_f32_16x16x32_bf16 v[10:13], v[182:185], v[206:209], v[10:13]
	v_mfma_f32_16x16x32_bf16 v[30:33], v[174:177], v[214:217], v[30:33]
	v_mfma_f32_16x16x32_bf16 v[26:29], v[182:185], v[214:217], v[26:29]
	s_setprio 0
	s_barrier
	s_cmp_lg_u32 s54, 28
	s_cbranch_scc1 .Lmy_p6_nox
	v_lshl_add_u32 v152, s26, 8, v1
	v_lshl_or_b32 v153, s49, 8, v161
	v_lshl_add_u32 v152, v152, 10, v153
	v_lshlrev_b32_e32 v150, 1, v152
	v_add_u32_e32 v151, 0x8000, v150
	global_load_dwordx4 v[226:229], v150, s[8:9]
	global_load_dwordx4 v[230:233], v150, s[10:11]
	global_load_dwordx4 v[234:237], v150, s[8:9] offset:256
	global_load_dwordx4 v[238:241], v150, s[10:11] offset:256
	global_load_dwordx4 v[242:245], v151, s[8:9]
	global_load_dwordx4 v[246:249], v151, s[10:11]
	global_load_dwordx4 v[250:253], v151, s[8:9] offset:256
	global_load_dwordx4 v[150:153], v151, s[10:11] offset:256

.Lmy_p6_wd_done:
	s_waitcnt lgkmcnt(0)
	s_barrier
	s_setprio 1
	s_waitcnt lgkmcnt(0)
	v_mfma_f32_16x16x32_bf16 v[62:65], v[130:133], v[186:189], v[62:65]
	v_mfma_f32_16x16x32_bf16 v[58:61], v[154:157], v[186:189], v[58:61]
	v_mfma_f32_16x16x32_bf16 v[46:49], v[130:133], v[194:197], v[46:49]
	v_mfma_f32_16x16x32_bf16 v[42:45], v[154:157], v[194:197], v[42:45]
	v_mfma_f32_16x16x32_bf16 v[6:9], v[130:133], v[202:205], v[6:9]
	v_mfma_f32_16x16x32_bf16 v[2:5], v[154:157], v[202:205], v[2:5]
	v_mfma_f32_16x16x32_bf16 v[22:25], v[130:133], v[210:213], v[22:25]
	v_mfma_f32_16x16x32_bf16 v[18:21], v[154:157], v[210:213], v[18:21]
	v_mfma_f32_16x16x32_bf16 v[62:65], v[134:137], v[190:193], v[62:65]
	v_mfma_f32_16x16x32_bf16 v[58:61], v[166:169], v[190:193], v[58:61]
	v_mfma_f32_16x16x32_bf16 v[46:49], v[134:137], v[198:201], v[46:49]
	v_mfma_f32_16x16x32_bf16 v[42:45], v[166:169], v[198:201], v[42:45]
	v_mfma_f32_16x16x32_bf16 v[6:9], v[134:137], v[206:209], v[6:9]
	v_mfma_f32_16x16x32_bf16 v[2:5], v[166:169], v[206:209], v[2:5]
	v_mfma_f32_16x16x32_bf16 v[22:25], v[134:137], v[214:217], v[22:25]
	v_mfma_f32_16x16x32_bf16 v[18:21], v[166:169], v[214:217], v[18:21]
	s_setprio 0
	s_setprio 1
	v_mfma_f32_16x16x32_bf16 v[54:57], v[170:173], v[186:189], v[54:57]
	v_mfma_f32_16x16x32_bf16 v[50:53], v[178:181], v[186:189], v[50:53]
	v_mfma_f32_16x16x32_bf16 v[38:41], v[170:173], v[194:197], v[38:41]
	v_mfma_f32_16x16x32_bf16 v[34:37], v[178:181], v[194:197], v[34:37]
	v_mfma_f32_16x16x32_bf16 v[14:17], v[170:173], v[202:205], v[14:17]
	v_mfma_f32_16x16x32_bf16 v[10:13], v[178:181], v[202:205], v[10:13]
	v_mfma_f32_16x16x32_bf16 v[30:33], v[170:173], v[210:213], v[30:33]
	v_mfma_f32_16x16x32_bf16 v[26:29], v[178:181], v[210:213], v[26:29]
	v_mfma_f32_16x16x32_bf16 v[54:57], v[174:177], v[190:193], v[54:57]
	v_mfma_f32_16x16x32_bf16 v[50:53], v[182:185], v[190:193], v[50:53]
	v_mfma_f32_16x16x32_bf16 v[38:41], v[174:177], v[198:201], v[38:41]
	v_mfma_f32_16x16x32_bf16 v[34:37], v[182:185], v[198:201], v[34:37]
	v_mfma_f32_16x16x32_bf16 v[14:17], v[174:177], v[206:209], v[14:17]
	v_mfma_f32_16x16x32_bf16 v[10:13], v[182:185], v[206:209], v[10:13]
	v_mfma_f32_16x16x32_bf16 v[30:33], v[174:177], v[214:217], v[30:33]
	v_mfma_f32_16x16x32_bf16 v[26:29], v[182:185], v[214:217], v[26:29]
	s_setprio 0
	s_barrier
	s_nop 0
	s_add_i32 s54, s54, 2
	s_add_u32 s0, s0, 0x100
	s_addc_u32 s1, s1, 0
	s_add_u32 s52, s52, 0x100
	s_addc_u32 s53, s53, 0
	s_cmp_gt_u32 s54, 29
	s_cbranch_scc0 .LBB0_796
	s_and_b64 vcc, exec, s[16:17]
	s_cbranch_vccz .LBB0_799
	s_barrier

.LBB0_875:
	ds_read_b128 v[130:133], v192
	ds_read_b128 v[134:137], v192 offset:1024
	ds_read_b128 v[138:141], v192 offset:2048
	ds_read_b128 v[142:145], v192 offset:3072
	ds_read_b128 v[146:149], v193
	ds_read_b128 v[150:153], v193 offset:1024
	ds_read_b128 v[154:157], v193 offset:2048
	ds_read_b128 v[158:161], v193 offset:3072
	s_add_u32 s38, s0, 0xfffc0080
	s_addc_u32 s39, s1, -1
	s_cmp_eq_u32 s62, 12
	s_cselect_b32 s41, s29, s39
	s_cselect_b32 s40, s37, s38
	s_cselect_b32 s39, s27, s61
	s_cselect_b32 s38, s59, s60
	v_lshl_add_u64 v[216:217], s[0:1], 0, v[170:171]
	s_add_i32 m0, s47, 0xc000
	ds_read_b128 v[178:181], v194
	ds_read_b128 v[182:185], v194 offset:1024
	ds_read_b128 v[186:189], v194 offset:2048
	ds_read_b128 v[196:199], v194 offset:3072
	ds_read_b128 v[200:203], v194 offset:4096
	ds_read_b128 v[204:207], v194 offset:5120
	ds_read_b128 v[208:211], v194 offset:6144
	ds_read_b128 v[212:215], v194 offset:7168
	global_load_lds_dwordx4 v[216:217], off
	v_lshl_add_u64 v[216:217], s[0:1], 0, v[172:173]
	s_add_i32 m0, s47, 0xe000
	s_nop 0
	global_load_lds_dwordx4 v[216:217], off
	s_waitcnt vmcnt(8)
	s_waitcnt lgkmcnt(0)
	s_barrier
	s_setprio 1
	s_waitcnt lgkmcnt(0)
	s_nop 0
	v_mfma_f32_16x16x32_bf16 v[126:129], v[130:133], v[178:181], v[126:129]
	v_mfma_f32_16x16x32_bf16 v[122:125], v[138:141], v[178:181], v[122:125]
	v_mfma_f32_16x16x32_bf16 v[118:121], v[130:133], v[186:189], v[118:121]
	v_mfma_f32_16x16x32_bf16 v[110:113], v[138:141], v[186:189], v[110:113]
	v_mfma_f32_16x16x32_bf16 v[94:97], v[130:133], v[200:203], v[94:97]
	v_mfma_f32_16x16x32_bf16 v[90:93], v[138:141], v[200:203], v[90:93]
	v_mfma_f32_16x16x32_bf16 v[82:85], v[130:133], v[208:211], v[82:85]
	v_mfma_f32_16x16x32_bf16 v[74:77], v[138:141], v[208:211], v[74:77]
	v_mfma_f32_16x16x32_bf16 v[126:129], v[134:137], v[182:185], v[126:129]
	v_mfma_f32_16x16x32_bf16 v[122:125], v[142:145], v[182:185], v[122:125]
	v_mfma_f32_16x16x32_bf16 v[118:121], v[134:137], v[196:199], v[118:121]
	v_mfma_f32_16x16x32_bf16 v[110:113], v[142:145], v[196:199], v[110:113]
	v_mfma_f32_16x16x32_bf16 v[94:97], v[134:137], v[204:207], v[94:97]
	v_mfma_f32_16x16x32_bf16 v[90:93], v[142:145], v[204:207], v[90:93]
	v_mfma_f32_16x16x32_bf16 v[82:85], v[134:137], v[212:215], v[82:85]
	v_mfma_f32_16x16x32_bf16 v[74:77], v[142:145], v[212:215], v[74:77]
	s_setprio 0
	s_setprio 1
	v_mfma_f32_16x16x32_bf16 v[114:117], v[146:149], v[178:181], v[114:117]
	v_mfma_f32_16x16x32_bf16 v[106:109], v[154:157], v[178:181], v[106:109]
	v_mfma_f32_16x16x32_bf16 v[102:105], v[146:149], v[186:189], v[102:105]
	v_mfma_f32_16x16x32_bf16 v[98:101], v[154:157], v[186:189], v[98:101]
	v_mfma_f32_16x16x32_bf16 v[86:89], v[146:149], v[200:203], v[86:89]
	v_mfma_f32_16x16x32_bf16 v[78:81], v[154:157], v[200:203], v[78:81]
	v_mfma_f32_16x16x32_bf16 v[70:73], v[146:149], v[208:211], v[70:73]
	v_mfma_f32_16x16x32_bf16 v[66:69], v[154:157], v[208:211], v[66:69]
	v_mfma_f32_16x16x32_bf16 v[114:117], v[150:153], v[182:185], v[114:117]
	v_mfma_f32_16x16x32_bf16 v[106:109], v[158:161], v[182:185], v[106:109]
	v_mfma_f32_16x16x32_bf16 v[102:105], v[150:153], v[196:199], v[102:105]
	v_mfma_f32_16x16x32_bf16 v[98:101], v[158:161], v[196:199], v[98:101]
	v_mfma_f32_16x16x32_bf16 v[86:89], v[150:153], v[204:207], v[86:89]
	v_mfma_f32_16x16x32_bf16 v[78:81], v[158:161], v[204:207], v[78:81]
	v_mfma_f32_16x16x32_bf16 v[70:73], v[150:153], v[212:215], v[70:73]
	v_mfma_f32_16x16x32_bf16 v[66:69], v[158:161], v[212:215], v[66:69]
	s_setprio 0
	s_barrier
	s_add_i32 s63, s56, s46
	v_lshl_add_u64 v[216:217], s[38:39], 0, v[164:165]
	s_mov_b32 m0, s63
	ds_read_b128 v[178:181], v194 offset:16384
	ds_read_b128 v[182:185], v194 offset:17408
	ds_read_b128 v[186:189], v194 offset:18432
	ds_read_b128 v[196:199], v194 offset:19456
	ds_read_b128 v[200:203], v194 offset:20480
	ds_read_b128 v[204:207], v194 offset:21504
	ds_read_b128 v[208:211], v194 offset:22528
	ds_read_b128 v[212:215], v194 offset:23552
	global_load_lds_dwordx4 v[216:217], off
	s_add_i32 m0, s63, 0x2000
	s_add_u32 s64, s38, 0x40000
	v_lshl_add_u64 v[218:219], s[38:39], 0, v[168:169]
	s_addc_u32 s65, s39, 0
	s_add_i32 s63, s57, s46
	global_load_lds_dwordx4 v[218:219], off
	v_lshl_add_u64 v[220:221], s[64:65], 0, v[164:165]
	s_mov_b32 m0, s63
	v_lshl_add_u64 v[222:223], s[40:41], 0, v[166:167]
	global_load_lds_dwordx4 v[220:221], off
	v_lshl_add_u64 v[220:221], s[64:65], 0, v[168:169]
	s_add_i32 m0, s63, 0x2000
	s_nop 0
	global_load_lds_dwordx4 v[220:221], off
	v_lshl_add_u64 v[220:221], s[40:41], 0, v[162:163]
	s_mov_b32 m0, s47
	s_nop 0
	global_load_lds_dwordx4 v[220:221], off
	s_mov_b32 m0, s48
	s_nop 0
	global_load_lds_dwordx4 v[222:223], off
	s_waitcnt vmcnt(8)
	s_waitcnt lgkmcnt(0)
	s_barrier
	s_setprio 1
	s_waitcnt lgkmcnt(0)
	s_nop 0
	v_mfma_f32_16x16x32_bf16 v[62:65], v[130:133], v[178:181], v[62:65]
	v_mfma_f32_16x16x32_bf16 v[58:61], v[138:141], v[178:181], v[58:61]
	v_mfma_f32_16x16x32_bf16 v[50:53], v[130:133], v[186:189], v[50:53]
	v_mfma_f32_16x16x32_bf16 v[42:45], v[138:141], v[186:189], v[42:45]
	v_mfma_f32_16x16x32_bf16 v[30:33], v[130:133], v[200:203], v[30:33]
	v_mfma_f32_16x16x32_bf16 v[26:29], v[138:141], v[200:203], v[26:29]
	v_mfma_f32_16x16x32_bf16 v[14:17], v[130:133], v[208:211], v[14:17]
	v_mfma_f32_16x16x32_bf16 v[10:13], v[138:141], v[208:211], v[10:13]
	v_mfma_f32_16x16x32_bf16 v[62:65], v[134:137], v[182:185], v[62:65]
	v_mfma_f32_16x16x32_bf16 v[58:61], v[142:145], v[182:185], v[58:61]
	v_mfma_f32_16x16x32_bf16 v[50:53], v[134:137], v[196:199], v[50:53]
	v_mfma_f32_16x16x32_bf16 v[42:45], v[142:145], v[196:199], v[42:45]
	v_mfma_f32_16x16x32_bf16 v[30:33], v[134:137], v[204:207], v[30:33]
	v_mfma_f32_16x16x32_bf16 v[26:29], v[142:145], v[204:207], v[26:29]
	v_mfma_f32_16x16x32_bf16 v[14:17], v[134:137], v[212:215], v[14:17]
	v_mfma_f32_16x16x32_bf16 v[10:13], v[142:145], v[212:215], v[10:13]
	s_setprio 0
	s_setprio 1
	v_mfma_f32_16x16x32_bf16 v[54:57], v[146:149], v[178:181], v[54:57]
	v_mfma_f32_16x16x32_bf16 v[46:49], v[154:157], v[178:181], v[46:49]
	v_mfma_f32_16x16x32_bf16 v[38:41], v[146:149], v[186:189], v[38:41]
	v_mfma_f32_16x16x32_bf16 v[34:37], v[154:157], v[186:189], v[34:37]
	v_mfma_f32_16x16x32_bf16 v[22:25], v[146:149], v[200:203], v[22:25]
	v_mfma_f32_16x16x32_bf16 v[18:21], v[154:157], v[200:203], v[18:21]
	v_mfma_f32_16x16x32_bf16 v[6:9], v[146:149], v[208:211], v[6:9]
	v_mfma_f32_16x16x32_bf16 v[2:5], v[154:157], v[208:211], v[2:5]
	v_mfma_f32_16x16x32_bf16 v[54:57], v[150:153], v[182:185], v[54:57]
	v_mfma_f32_16x16x32_bf16 v[46:49], v[158:161], v[182:185], v[46:49]
	v_mfma_f32_16x16x32_bf16 v[38:41], v[150:153], v[196:199], v[38:41]
	v_mfma_f32_16x16x32_bf16 v[34:37], v[158:161], v[196:199], v[34:37]
	v_mfma_f32_16x16x32_bf16 v[22:25], v[150:153], v[204:207], v[22:25]
	v_mfma_f32_16x16x32_bf16 v[18:21], v[158:161], v[204:207], v[18:21]
	v_mfma_f32_16x16x32_bf16 v[6:9], v[150:153], v[212:215], v[6:9]
	v_mfma_f32_16x16x32_bf16 v[2:5], v[158:161], v[212:215], v[2:5]
	s_setprio 0
	s_barrier
	s_add_i32 s63, 0, 0x18000
	s_add_i32 s64, 0, 0x1c000
	v_add_u32_e32 v142, s63, v190
	v_add_u32_e32 v158, s64, v190
	ds_read_b128 v[130:133], v142
	ds_read_b128 v[134:137], v142 offset:1024
	ds_read_b128 v[138:141], v142 offset:2048
	ds_read_b128 v[142:145], v142 offset:3072
	ds_read_b128 v[146:149], v158
	ds_read_b128 v[150:153], v158 offset:1024
	ds_read_b128 v[154:157], v158 offset:2048
	ds_read_b128 v[158:161], v158 offset:3072
	s_add_u32 s40, s40, 0x40000
	s_addc_u32 s41, s41, 0
	s_mov_b32 m0, s49
	v_lshl_add_u64 v[224:225], s[40:41], 0, v[162:163]
	ds_read_b128 v[178:181], v194 offset:32768
	ds_read_b128 v[182:185], v194 offset:33792
	ds_read_b128 v[186:189], v194 offset:34816
	ds_read_b128 v[196:199], v194 offset:35840
	ds_read_b128 v[200:203], v194 offset:36864
	ds_read_b128 v[204:207], v194 offset:37888
	ds_read_b128 v[208:211], v194 offset:38912
	ds_read_b128 v[212:215], v194 offset:39936
	global_load_lds_dwordx4 v[224:225], off
	v_lshl_add_u64 v[224:225], s[40:41], 0, v[166:167]
	s_mov_b32 m0, s50
	s_nop 0
	global_load_lds_dwordx4 v[224:225], off
	s_waitcnt vmcnt(8)
	s_waitcnt lgkmcnt(0)
	s_barrier
	s_setprio 1
	s_waitcnt lgkmcnt(0)
	s_nop 0
	v_mfma_f32_16x16x32_bf16 v[126:129], v[130:133], v[178:181], v[126:129]
	v_mfma_f32_16x16x32_bf16 v[122:125], v[138:141], v[178:181], v[122:125]
	v_mfma_f32_16x16x32_bf16 v[118:121], v[130:133], v[186:189], v[118:121]
	v_mfma_f32_16x16x32_bf16 v[110:113], v[138:141], v[186:189], v[110:113]
	v_mfma_f32_16x16x32_bf16 v[94:97], v[130:133], v[200:203], v[94:97]
	v_mfma_f32_16x16x32_bf16 v[90:93], v[138:141], v[200:203], v[90:93]
	v_mfma_f32_16x16x32_bf16 v[82:85], v[130:133], v[208:211], v[82:85]
	v_mfma_f32_16x16x32_bf16 v[74:77], v[138:141], v[208:211], v[74:77]
	v_mfma_f32_16x16x32_bf16 v[126:129], v[134:137], v[182:185], v[126:129]
	v_mfma_f32_16x16x32_bf16 v[122:125], v[142:145], v[182:185], v[122:125]
	v_mfma_f32_16x16x32_bf16 v[118:121], v[134:137], v[196:199], v[118:121]
	v_mfma_f32_16x16x32_bf16 v[110:113], v[142:145], v[196:199], v[110:113]
	v_mfma_f32_16x16x32_bf16 v[94:97], v[134:137], v[204:207], v[94:97]
	v_mfma_f32_16x16x32_bf16 v[90:93], v[142:145], v[204:207], v[90:93]
	v_mfma_f32_16x16x32_bf16 v[82:85], v[134:137], v[212:215], v[82:85]
	v_mfma_f32_16x16x32_bf16 v[74:77], v[142:145], v[212:215], v[74:77]
	s_setprio 0
	s_setprio 1
	v_mfma_f32_16x16x32_bf16 v[114:117], v[146:149], v[178:181], v[114:117]
	v_mfma_f32_16x16x32_bf16 v[106:109], v[154:157], v[178:181], v[106:109]
	v_mfma_f32_16x16x32_bf16 v[102:105], v[146:149], v[186:189], v[102:105]
	v_mfma_f32_16x16x32_bf16 v[98:101], v[154:157], v[186:189], v[98:101]
	v_mfma_f32_16x16x32_bf16 v[86:89], v[146:149], v[200:203], v[86:89]
	v_mfma_f32_16x16x32_bf16 v[78:81], v[154:157], v[200:203], v[78:81]
	v_mfma_f32_16x16x32_bf16 v[70:73], v[146:149], v[208:211], v[70:73]
	v_mfma_f32_16x16x32_bf16 v[66:69], v[154:157], v[208:211], v[66:69]
	v_mfma_f32_16x16x32_bf16 v[114:117], v[150:153], v[182:185], v[114:117]
	v_mfma_f32_16x16x32_bf16 v[106:109], v[158:161], v[182:185], v[106:109]
	v_mfma_f32_16x16x32_bf16 v[102:105], v[150:153], v[196:199], v[102:105]
	v_mfma_f32_16x16x32_bf16 v[98:101], v[158:161], v[196:199], v[98:101]
	v_mfma_f32_16x16x32_bf16 v[86:89], v[150:153], v[204:207], v[86:89]
	v_mfma_f32_16x16x32_bf16 v[78:81], v[158:161], v[204:207], v[78:81]
	v_mfma_f32_16x16x32_bf16 v[70:73], v[150:153], v[212:215], v[70:73]
	v_mfma_f32_16x16x32_bf16 v[66:69], v[158:161], v[212:215], v[66:69]
	s_setprio 0
	s_barrier
	s_add_i32 s40, s63, s46
	v_lshl_add_u64 v[216:217], v[216:217], 0, s[18:19]
	s_mov_b32 m0, s40
	ds_read_b128 v[178:181], v194 offset:49152
	ds_read_b128 v[182:185], v194 offset:50176
	ds_read_b128 v[186:189], v194 offset:51200
	ds_read_b128 v[196:199], v194 offset:52224
	ds_read_b128 v[200:203], v194 offset:53248
	ds_read_b128 v[204:207], v194 offset:54272
	ds_read_b128 v[208:211], v194 offset:55296
	ds_read_b128 v[212:215], v194 offset:56320
	global_load_lds_dwordx4 v[216:217], off
	s_add_i32 m0, s40, 0x2000
	s_add_u32 s38, s38, 0x40080
	v_lshl_add_u64 v[216:217], v[218:219], 0, s[18:19]
	s_addc_u32 s39, s39, 0
	s_add_i32 s40, s64, s46
	global_load_lds_dwordx4 v[216:217], off
	v_lshl_add_u64 v[216:217], s[38:39], 0, v[164:165]
	s_mov_b32 m0, s40
	s_nop 0
	global_load_lds_dwordx4 v[216:217], off
	v_lshl_add_u64 v[216:217], s[38:39], 0, v[168:169]
	s_add_i32 m0, s40, 0x2000
	s_nop 0
	global_load_lds_dwordx4 v[216:217], off
	v_lshl_add_u64 v[216:217], v[220:221], 0, s[18:19]
	s_mov_b32 m0, s52
	s_nop 0
	global_load_lds_dwordx4 v[216:217], off
	v_lshl_add_u64 v[216:217], v[222:223], 0, s[18:19]
	s_mov_b32 m0, s53
	s_nop 0
	global_load_lds_dwordx4 v[216:217], off
	s_waitcnt vmcnt(8)
	s_waitcnt lgkmcnt(0)
	s_barrier
	s_setprio 1
	s_waitcnt lgkmcnt(0)
	v_mfma_f32_16x16x32_bf16 v[62:65], v[130:133], v[178:181], v[62:65]
	v_mfma_f32_16x16x32_bf16 v[58:61], v[138:141], v[178:181], v[58:61]
	v_mfma_f32_16x16x32_bf16 v[50:53], v[130:133], v[186:189], v[50:53]
	v_mfma_f32_16x16x32_bf16 v[42:45], v[138:141], v[186:189], v[42:45]
	v_mfma_f32_16x16x32_bf16 v[30:33], v[130:133], v[200:203], v[30:33]
	v_mfma_f32_16x16x32_bf16 v[26:29], v[138:141], v[200:203], v[26:29]
	v_mfma_f32_16x16x32_bf16 v[14:17], v[130:133], v[208:211], v[14:17]
	v_mfma_f32_16x16x32_bf16 v[10:13], v[138:141], v[208:211], v[10:13]
	v_mfma_f32_16x16x32_bf16 v[62:65], v[134:137], v[182:185], v[62:65]
	v_mfma_f32_16x16x32_bf16 v[58:61], v[142:145], v[182:185], v[58:61]
	v_mfma_f32_16x16x32_bf16 v[50:53], v[134:137], v[196:199], v[50:53]
	v_mfma_f32_16x16x32_bf16 v[42:45], v[142:145], v[196:199], v[42:45]
	v_mfma_f32_16x16x32_bf16 v[30:33], v[134:137], v[204:207], v[30:33]
	v_mfma_f32_16x16x32_bf16 v[26:29], v[142:145], v[204:207], v[26:29]
	v_mfma_f32_16x16x32_bf16 v[14:17], v[134:137], v[212:215], v[14:17]
	v_mfma_f32_16x16x32_bf16 v[10:13], v[142:145], v[212:215], v[10:13]
	s_setprio 0
	s_setprio 1
	v_mfma_f32_16x16x32_bf16 v[54:57], v[146:149], v[178:181], v[54:57]
	v_mfma_f32_16x16x32_bf16 v[46:49], v[154:157], v[178:181], v[46:49]
	v_mfma_f32_16x16x32_bf16 v[38:41], v[146:149], v[186:189], v[38:41]
	v_mfma_f32_16x16x32_bf16 v[34:37], v[154:157], v[186:189], v[34:37]
	v_mfma_f32_16x16x32_bf16 v[22:25], v[146:149], v[200:203], v[22:25]
	v_mfma_f32_16x16x32_bf16 v[18:21], v[154:157], v[200:203], v[18:21]
	v_mfma_f32_16x16x32_bf16 v[6:9], v[146:149], v[208:211], v[6:9]
	v_mfma_f32_16x16x32_bf16 v[2:5], v[154:157], v[208:211], v[2:5]
	v_mfma_f32_16x16x32_bf16 v[54:57], v[150:153], v[182:185], v[54:57]
	v_mfma_f32_16x16x32_bf16 v[46:49], v[158:161], v[182:185], v[46:49]
	v_mfma_f32_16x16x32_bf16 v[38:41], v[150:153], v[196:199], v[38:41]
	v_mfma_f32_16x16x32_bf16 v[34:37], v[158:161], v[196:199], v[34:37]
	v_mfma_f32_16x16x32_bf16 v[22:25], v[150:153], v[204:207], v[22:25]
	v_mfma_f32_16x16x32_bf16 v[18:21], v[158:161], v[204:207], v[18:21]
	v_mfma_f32_16x16x32_bf16 v[6:9], v[150:153], v[212:215], v[6:9]
	v_mfma_f32_16x16x32_bf16 v[2:5], v[158:161], v[212:215], v[2:5]
	s_setprio 0
	s_barrier
	s_nop 0
	s_add_i32 s62, s62, 2
	s_add_u32 s0, s0, 0x100
	s_addc_u32 s1, s1, 0
	s_add_u32 s60, s60, 0x100
	s_addc_u32 s61, s61, 0
	s_cmp_gt_u32 s62, 13
	s_cbranch_scc0 .LBB0_875
	s_and_b64 vcc, exec, s[20:21]
	s_cbranch_vccz .LBB0_878
	s_barrier

.LBB0_967:
	s_cmp_lg_u32 s12, 0
	v_mov_b32_e32 v133, v137
	v_mov_b32_e32 v135, v137
	v_mov_b32_e32 v131, v137
	s_cbranch_scc0 .LBB0_977
	ds_read_b128 v[2:5], v151
	ds_read_b128 v[6:9], v151 offset:1024
	ds_read_b128 v[10:13], v151 offset:2048
	ds_read_b128 v[14:17], v151 offset:3072
	ds_read_b128 v[18:21], v153
	ds_read_b128 v[22:25], v153 offset:1024
	ds_read_b128 v[26:29], v153 offset:2048
	ds_read_b128 v[30:33], v153 offset:3072
	ds_read_b128 v[34:37], v155
	ds_read_b128 v[38:41], v155 offset:1024
	ds_read_b128 v[42:45], v155 offset:2048
	ds_read_b128 v[46:49], v155 offset:3072
	ds_read_b128 v[50:53], v155 offset:4096
	ds_read_b128 v[54:57], v155 offset:5120
	ds_read_b128 v[58:61], v155 offset:6144
	ds_read_b128 v[62:65], v155 offset:7168
	s_waitcnt vmcnt(24)
	s_waitcnt lgkmcnt(0)
	s_barrier
	s_setprio 1
	s_waitcnt lgkmcnt(0)
	s_nop 0
	v_mfma_f32_16x16x32_bf16 v[90:93], v[2:5], v[58:61], 0
	v_mfma_f32_16x16x32_bf16 v[66:69], v[2:5], v[34:37], 0
	v_mfma_f32_16x16x32_bf16 v[70:73], v[10:13], v[34:37], 0
	v_mfma_f32_16x16x32_bf16 v[74:77], v[2:5], v[42:45], 0
	v_mfma_f32_16x16x32_bf16 v[78:81], v[10:13], v[42:45], 0
	v_mfma_f32_16x16x32_bf16 v[82:85], v[2:5], v[50:53], 0
	v_mfma_f32_16x16x32_bf16 v[86:89], v[10:13], v[50:53], 0
	v_mfma_f32_16x16x32_bf16 v[98:101], v[6:9], v[62:65], v[90:93]
	v_mfma_f32_16x16x32_bf16 v[90:93], v[10:13], v[58:61], 0
	v_mfma_f32_16x16x32_bf16 v[66:69], v[6:9], v[38:41], v[66:69]
	v_mfma_f32_16x16x32_bf16 v[70:73], v[14:17], v[38:41], v[70:73]
	v_mfma_f32_16x16x32_bf16 v[74:77], v[6:9], v[46:49], v[74:77]
	v_mfma_f32_16x16x32_bf16 v[78:81], v[14:17], v[46:49], v[78:81]
	v_mfma_f32_16x16x32_bf16 v[82:85], v[6:9], v[54:57], v[82:85]
	v_mfma_f32_16x16x32_bf16 v[86:89], v[14:17], v[54:57], v[86:89]
	v_mfma_f32_16x16x32_bf16 v[102:105], v[14:17], v[62:65], v[90:93]
	s_setprio 0
	s_setprio 1
	v_mfma_f32_16x16x32_bf16 v[90:93], v[18:21], v[34:37], 0
	v_mfma_f32_16x16x32_bf16 v[34:37], v[26:29], v[34:37], 0
	v_mfma_f32_16x16x32_bf16 v[114:117], v[22:25], v[38:41], v[90:93]
	v_mfma_f32_16x16x32_bf16 v[34:37], v[30:33], v[38:41], v[34:37]
	v_mfma_f32_16x16x32_bf16 v[38:41], v[18:21], v[42:45], 0
	v_mfma_f32_16x16x32_bf16 v[42:45], v[26:29], v[42:45], 0
	v_mfma_f32_16x16x32_bf16 v[38:41], v[22:25], v[46:49], v[38:41]
	v_mfma_f32_16x16x32_bf16 v[42:45], v[30:33], v[46:49], v[42:45]
	v_mfma_f32_16x16x32_bf16 v[46:49], v[18:21], v[50:53], 0
	v_mfma_f32_16x16x32_bf16 v[50:53], v[26:29], v[50:53], 0
	v_mfma_f32_16x16x32_bf16 v[46:49], v[22:25], v[54:57], v[46:49]
	v_mfma_f32_16x16x32_bf16 v[50:53], v[30:33], v[54:57], v[50:53]
	v_mfma_f32_16x16x32_bf16 v[54:57], v[18:21], v[58:61], 0
	v_mfma_f32_16x16x32_bf16 v[58:61], v[26:29], v[58:61], 0
	v_mfma_f32_16x16x32_bf16 v[54:57], v[22:25], v[62:65], v[54:57]
	v_mfma_f32_16x16x32_bf16 v[58:61], v[30:33], v[62:65], v[58:61]
	s_setprio 0
	s_barrier
	v_lshl_add_u64 v[248:249], s[0:1], 0, v[132:133]
	s_add_i32 s8, s57, s45
	v_lshl_add_u64 v[142:143], v[248:249], 0, s[24:25]
	s_mov_b32 m0, s8
	ds_read_b128 v[62:65], v155 offset:16384
	ds_read_b128 v[90:93], v155 offset:17408
	ds_read_b128 v[94:97], v155 offset:18432
	ds_read_b128 v[106:109], v155 offset:19456
	ds_read_b128 v[110:113], v155 offset:20480
	ds_read_b128 v[118:121], v155 offset:21504
	ds_read_b128 v[122:125], v155 offset:22528
	ds_read_b128 v[126:129], v155 offset:23552
	global_load_lds_dwordx4 v[142:143], off
	s_add_i32 m0, s8, 0x2000
	v_lshl_add_u64 v[250:251], s[0:1], 0, v[136:137]
	s_add_u32 s8, s0, 0x10100
	v_lshl_add_u64 v[142:143], v[250:251], 0, s[24:25]
	s_addc_u32 s9, s1, 0
	s_add_i32 s12, s58, s45
	global_load_lds_dwordx4 v[142:143], off
	s_mov_b32 m0, s12
	v_lshl_add_u64 v[252:253], s[6:7], 0, v[130:131]
	global_load_lds_dwordx4 v132, s[8:9]
	s_add_i32 m0, s12, 0x2000
	v_lshl_add_u64 v[142:143], v[252:253], 0, s[24:25]
	global_load_lds_dwordx4 v136, s[8:9]
	s_mov_b32 m0, s46
	v_lshl_add_u64 v[138:139], s[6:7], 0, v[134:135]
	global_load_lds_dwordx4 v[142:143], off
	v_lshl_add_u64 v[142:143], v[138:139], 0, s[24:25]
	s_mov_b32 m0, s47
	s_nop 0
	global_load_lds_dwordx4 v[142:143], off
	s_waitcnt vmcnt(24)
	s_waitcnt lgkmcnt(0)
	s_barrier
	s_setprio 1
	s_waitcnt lgkmcnt(0)
	s_nop 0
	v_mfma_f32_16x16x32_bf16 v[142:145], v[2:5], v[62:65], 0
	v_mfma_f32_16x16x32_bf16 v[160:163], v[2:5], v[94:97], 0
	v_mfma_f32_16x16x32_bf16 v[168:171], v[2:5], v[110:113], 0
	v_mfma_f32_16x16x32_bf16 v[2:5], v[2:5], v[122:125], 0
	v_mfma_f32_16x16x32_bf16 v[142:145], v[6:9], v[90:93], v[142:145]
	v_mfma_f32_16x16x32_bf16 v[160:163], v[6:9], v[106:109], v[160:163]
	v_mfma_f32_16x16x32_bf16 v[168:171], v[6:9], v[118:121], v[168:171]
	v_mfma_f32_16x16x32_bf16 v[2:5], v[6:9], v[126:129], v[2:5]
	v_mfma_f32_16x16x32_bf16 v[6:9], v[10:13], v[122:125], 0
	v_mfma_f32_16x16x32_bf16 v[156:159], v[10:13], v[62:65], 0
	v_mfma_f32_16x16x32_bf16 v[164:167], v[10:13], v[94:97], 0
	v_mfma_f32_16x16x32_bf16 v[172:175], v[10:13], v[110:113], 0
	v_mfma_f32_16x16x32_bf16 v[6:9], v[14:17], v[126:129], v[6:9]
	v_mfma_f32_16x16x32_bf16 v[156:159], v[14:17], v[90:93], v[156:159]
	v_mfma_f32_16x16x32_bf16 v[164:167], v[14:17], v[106:109], v[164:167]
	v_mfma_f32_16x16x32_bf16 v[172:175], v[14:17], v[118:121], v[172:175]
	s_setprio 0
	s_setprio 1
	v_mfma_f32_16x16x32_bf16 v[10:13], v[18:21], v[62:65], 0
	v_mfma_f32_16x16x32_bf16 v[176:179], v[22:25], v[90:93], v[10:13]
	v_mfma_f32_16x16x32_bf16 v[10:13], v[26:29], v[62:65], 0
	v_mfma_f32_16x16x32_bf16 v[180:183], v[30:33], v[90:93], v[10:13]
	v_mfma_f32_16x16x32_bf16 v[10:13], v[18:21], v[94:97], 0
	v_mfma_f32_16x16x32_bf16 v[184:187], v[22:25], v[106:109], v[10:13]
	v_mfma_f32_16x16x32_bf16 v[10:13], v[26:29], v[94:97], 0
	v_mfma_f32_16x16x32_bf16 v[188:191], v[30:33], v[106:109], v[10:13]
	v_mfma_f32_16x16x32_bf16 v[10:13], v[18:21], v[110:113], 0
	v_mfma_f32_16x16x32_bf16 v[192:195], v[22:25], v[118:121], v[10:13]
	v_mfma_f32_16x16x32_bf16 v[10:13], v[26:29], v[110:113], 0
	v_mfma_f32_16x16x32_bf16 v[196:199], v[30:33], v[118:121], v[10:13]
	v_mfma_f32_16x16x32_bf16 v[10:13], v[18:21], v[122:125], 0
	v_mfma_f32_16x16x32_bf16 v[200:203], v[22:25], v[126:129], v[10:13]
	v_mfma_f32_16x16x32_bf16 v[10:13], v[26:29], v[122:125], 0
	v_mfma_f32_16x16x32_bf16 v[204:207], v[30:33], v[126:129], v[10:13]
	s_setprio 0
	s_barrier
	s_add_i32 s12, 0, 0x18000
	s_add_i32 s35, 0, 0x1c000
	v_add_u32_e32 v22, s12, v149
	v_add_u32_e32 v26, s35, v149
	s_nop 0
	ds_read_b128 v[10:13], v22
	ds_read_b128 v[14:17], v22 offset:1024
	ds_read_b128 v[18:21], v22 offset:2048
	ds_read_b128 v[22:25], v22 offset:3072
	ds_read_b128 v[208:211], v26
	ds_read_b128 v[212:215], v26 offset:1024
	ds_read_b128 v[216:219], v26 offset:2048
	ds_read_b128 v[220:223], v26 offset:3072
	s_add_u32 s8, s6, 0x40100
	s_addc_u32 s9, s7, 0
	s_mov_b32 m0, s48
	ds_read_b128 v[26:29], v155 offset:32768
	ds_read_b128 v[30:33], v155 offset:33792
	ds_read_b128 v[62:65], v155 offset:34816
	ds_read_b128 v[224:227], v155 offset:35840
	ds_read_b128 v[228:231], v155 offset:36864
	ds_read_b128 v[232:235], v155 offset:37888
	ds_read_b128 v[236:239], v155 offset:38912
	ds_read_b128 v[240:243], v155 offset:39936
	global_load_lds_dwordx4 v130, s[8:9]
	s_mov_b32 m0, s49
	s_nop 0
	global_load_lds_dwordx4 v134, s[8:9]
	s_waitcnt vmcnt(24)
	s_waitcnt lgkmcnt(0)
	s_barrier
	s_setprio 1
	s_waitcnt lgkmcnt(0)
	v_mfma_f32_16x16x32_bf16 v[66:69], v[10:13], v[26:29], v[66:69]
	v_mfma_f32_16x16x32_bf16 v[126:129], v[14:17], v[30:33], v[66:69]
	v_mfma_f32_16x16x32_bf16 v[66:69], v[18:21], v[26:29], v[70:73]
	v_mfma_f32_16x16x32_bf16 v[122:125], v[22:25], v[30:33], v[66:69]
	v_mfma_f32_16x16x32_bf16 v[66:69], v[10:13], v[62:65], v[74:77]
	v_mfma_f32_16x16x32_bf16 v[110:113], v[14:17], v[224:227], v[66:69]
	v_mfma_f32_16x16x32_bf16 v[66:69], v[18:21], v[62:65], v[78:81]
	v_mfma_f32_16x16x32_bf16 v[106:109], v[22:25], v[224:227], v[66:69]
	v_mfma_f32_16x16x32_bf16 v[66:69], v[10:13], v[228:231], v[82:85]
	v_mfma_f32_16x16x32_bf16 v[94:97], v[14:17], v[232:235], v[66:69]
	v_mfma_f32_16x16x32_bf16 v[66:69], v[18:21], v[228:231], v[86:89]
	v_mfma_f32_16x16x32_bf16 v[90:93], v[22:25], v[232:235], v[66:69]
	v_mfma_f32_16x16x32_bf16 v[66:69], v[10:13], v[236:239], v[98:101]
	v_mfma_f32_16x16x32_bf16 v[78:81], v[14:17], v[240:243], v[66:69]
	v_mfma_f32_16x16x32_bf16 v[66:69], v[18:21], v[236:239], v[102:105]
	v_mfma_f32_16x16x32_bf16 v[74:77], v[22:25], v[240:243], v[66:69]
	s_setprio 0
	s_setprio 1
	v_mfma_f32_16x16x32_bf16 v[66:69], v[208:211], v[26:29], v[114:117]
	v_mfma_f32_16x16x32_bf16 v[26:29], v[216:219], v[26:29], v[34:37]
	v_mfma_f32_16x16x32_bf16 v[114:117], v[220:223], v[30:33], v[26:29]
	v_mfma_f32_16x16x32_bf16 v[26:29], v[208:211], v[62:65], v[38:41]
	v_mfma_f32_16x16x32_bf16 v[102:105], v[212:215], v[224:227], v[26:29]
	v_mfma_f32_16x16x32_bf16 v[26:29], v[216:219], v[62:65], v[42:45]
	v_mfma_f32_16x16x32_bf16 v[98:101], v[220:223], v[224:227], v[26:29]
	v_mfma_f32_16x16x32_bf16 v[26:29], v[208:211], v[228:231], v[46:49]
	v_mfma_f32_16x16x32_bf16 v[86:89], v[212:215], v[232:235], v[26:29]
	v_mfma_f32_16x16x32_bf16 v[26:29], v[216:219], v[228:231], v[50:53]
	v_mfma_f32_16x16x32_bf16 v[82:85], v[220:223], v[232:235], v[26:29]
	v_mfma_f32_16x16x32_bf16 v[26:29], v[208:211], v[236:239], v[54:57]
	v_mfma_f32_16x16x32_bf16 v[70:73], v[212:215], v[240:243], v[26:29]
	v_mfma_f32_16x16x32_bf16 v[26:29], v[216:219], v[236:239], v[58:61]
	v_mfma_f32_16x16x32_bf16 v[118:121], v[212:215], v[30:33], v[66:69]
	v_mfma_f32_16x16x32_bf16 v[66:69], v[220:223], v[240:243], v[26:29]
	s_setprio 0
	s_barrier
	s_add_i32 s8, s12, s45
	s_nop 2
	v_lshl_add_u64 v[26:27], v[248:249], 0, s[26:27]
	s_mov_b32 m0, s8
	ds_read_b128 v[34:37], v155 offset:49152
	ds_read_b128 v[38:41], v155 offset:50176
	ds_read_b128 v[224:227], v155 offset:51200
	ds_read_b128 v[228:231], v155 offset:52224
	ds_read_b128 v[232:235], v155 offset:53248
	ds_read_b128 v[236:239], v155 offset:54272
	ds_read_b128 v[240:243], v155 offset:55296
	ds_read_b128 v[244:247], v155 offset:56320
	global_load_lds_dwordx4 v[26:27], off
	s_add_i32 m0, s8, 0x2000
	s_add_u32 s8, s0, 0x10180
	v_lshl_add_u64 v[26:27], v[250:251], 0, s[26:27]
	s_addc_u32 s9, s1, 0
	s_add_i32 s12, s35, s45
	global_load_lds_dwordx4 v[26:27], off
	s_mov_b32 m0, s12
	v_lshl_add_u64 v[26:27], v[252:253], 0, s[26:27]
	global_load_lds_dwordx4 v132, s[8:9]
	s_add_i32 m0, s12, 0x2000
	s_nop 0
	global_load_lds_dwordx4 v136, s[8:9]
	s_mov_b32 m0, s53
	s_nop 0
	global_load_lds_dwordx4 v[26:27], off
	v_lshl_add_u64 v[26:27], v[138:139], 0, s[26:27]
	s_mov_b32 m0, s54
	s_nop 0
	global_load_lds_dwordx4 v[26:27], off
	s_waitcnt vmcnt(8)
	s_waitcnt lgkmcnt(0)
	s_barrier
	s_setprio 1
	s_waitcnt lgkmcnt(0)
	v_mfma_f32_16x16x32_bf16 v[26:29], v[10:13], v[34:37], v[142:145]
	v_mfma_f32_16x16x32_bf16 v[62:65], v[14:17], v[38:41], v[26:29]
	v_mfma_f32_16x16x32_bf16 v[26:29], v[18:21], v[34:37], v[156:159]
	v_mfma_f32_16x16x32_bf16 v[58:61], v[22:25], v[38:41], v[26:29]
	v_mfma_f32_16x16x32_bf16 v[26:29], v[10:13], v[224:227], v[160:163]
	v_mfma_f32_16x16x32_bf16 v[46:49], v[14:17], v[228:231], v[26:29]
	v_mfma_f32_16x16x32_bf16 v[26:29], v[18:21], v[224:227], v[164:167]
	v_mfma_f32_16x16x32_bf16 v[42:45], v[22:25], v[228:231], v[26:29]
	v_mfma_f32_16x16x32_bf16 v[26:29], v[10:13], v[232:235], v[168:171]
	v_mfma_f32_16x16x32_bf16 v[2:5], v[10:13], v[240:243], v[2:5]
	v_mfma_f32_16x16x32_bf16 v[30:33], v[14:17], v[236:239], v[26:29]
	v_mfma_f32_16x16x32_bf16 v[26:29], v[18:21], v[232:235], v[172:175]
	v_mfma_f32_16x16x32_bf16 v[14:17], v[14:17], v[244:247], v[2:5]
	v_mfma_f32_16x16x32_bf16 v[2:5], v[18:21], v[240:243], v[6:9]
	v_mfma_f32_16x16x32_bf16 v[26:29], v[22:25], v[236:239], v[26:29]
	v_mfma_f32_16x16x32_bf16 v[10:13], v[22:25], v[244:247], v[2:5]
	s_setprio 0
	s_setprio 1
	v_mfma_f32_16x16x32_bf16 v[2:5], v[208:211], v[34:37], v[176:179]
	v_mfma_f32_16x16x32_bf16 v[54:57], v[212:215], v[38:41], v[2:5]
	v_mfma_f32_16x16x32_bf16 v[2:5], v[216:219], v[34:37], v[180:183]
	v_mfma_f32_16x16x32_bf16 v[50:53], v[220:223], v[38:41], v[2:5]
	v_mfma_f32_16x16x32_bf16 v[2:5], v[208:211], v[224:227], v[184:187]
	v_mfma_f32_16x16x32_bf16 v[38:41], v[212:215], v[228:231], v[2:5]
	v_mfma_f32_16x16x32_bf16 v[2:5], v[216:219], v[224:227], v[188:191]
	v_mfma_f32_16x16x32_bf16 v[34:37], v[220:223], v[228:231], v[2:5]
	v_mfma_f32_16x16x32_bf16 v[2:5], v[208:211], v[232:235], v[192:195]
	v_mfma_f32_16x16x32_bf16 v[22:25], v[212:215], v[236:239], v[2:5]
	v_mfma_f32_16x16x32_bf16 v[2:5], v[216:219], v[232:235], v[196:199]
	v_mfma_f32_16x16x32_bf16 v[18:21], v[220:223], v[236:239], v[2:5]
	v_mfma_f32_16x16x32_bf16 v[2:5], v[208:211], v[240:243], v[200:203]
	v_mfma_f32_16x16x32_bf16 v[6:9], v[212:215], v[244:247], v[2:5]
	v_mfma_f32_16x16x32_bf16 v[2:5], v[216:219], v[240:243], v[204:207]
	v_mfma_f32_16x16x32_bf16 v[2:5], v[220:223], v[244:247], v[2:5]
	s_setprio 0
	s_barrier
	s_mov_b32 s8, 2
	s_cbranch_execnz .LBB0_970

.Lmy_p8_noload:
	s_add_i32 s70, s57, s45
	v_lshl_add_u64 v[138:139], s[6:7], 0, v[132:133]
	s_mov_b32 m0, s70
	ds_read_b128 v[188:191], v155 offset:16384
	ds_read_b128 v[192:195], v155 offset:17408
	ds_read_b128 v[196:199], v155 offset:18432
	ds_read_b128 v[200:203], v155 offset:19456
	ds_read_b128 v[204:207], v155 offset:20480
	ds_read_b128 v[208:211], v155 offset:21504
	ds_read_b128 v[212:215], v155 offset:22528
	ds_read_b128 v[216:219], v155 offset:23552
	global_load_lds_dwordx4 v[138:139], off
	s_add_i32 m0, s70, 0x2000
	s_add_u32 s70, s6, 0x10000
	v_lshl_add_u64 v[220:221], s[6:7], 0, v[136:137]
	s_addc_u32 s71, s7, 0
	s_add_i32 s72, s58, s45
	global_load_lds_dwordx4 v[220:221], off
	v_lshl_add_u64 v[222:223], s[70:71], 0, v[132:133]
	s_mov_b32 m0, s72
	v_lshl_add_u64 v[224:225], s[8:9], 0, v[134:135]
	global_load_lds_dwordx4 v[222:223], off
	v_lshl_add_u64 v[222:223], s[70:71], 0, v[136:137]
	s_add_i32 m0, s72, 0x2000
	s_nop 0
	global_load_lds_dwordx4 v[222:223], off
	v_lshl_add_u64 v[222:223], s[8:9], 0, v[130:131]
	s_mov_b32 m0, s46
	s_nop 0
	global_load_lds_dwordx4 v[222:223], off
	s_mov_b32 m0, s47
	s_nop 0
	global_load_lds_dwordx4 v[224:225], off
	s_waitcnt vmcnt(8)
	s_waitcnt lgkmcnt(0)
	s_barrier
	s_setprio 1
	s_waitcnt lgkmcnt(0)
	v_mfma_f32_16x16x32_bf16 v[62:65], v[156:159], v[188:191], v[62:65]
	v_mfma_f32_16x16x32_bf16 v[58:61], v[164:167], v[188:191], v[58:61]
	v_mfma_f32_16x16x32_bf16 v[46:49], v[156:159], v[196:199], v[46:49]
	v_mfma_f32_16x16x32_bf16 v[42:45], v[164:167], v[196:199], v[42:45]
	v_mfma_f32_16x16x32_bf16 v[30:33], v[156:159], v[204:207], v[30:33]
	v_mfma_f32_16x16x32_bf16 v[26:29], v[164:167], v[204:207], v[26:29]
	v_mfma_f32_16x16x32_bf16 v[14:17], v[156:159], v[212:215], v[14:17]
	v_mfma_f32_16x16x32_bf16 v[10:13], v[164:167], v[212:215], v[10:13]
	v_mfma_f32_16x16x32_bf16 v[62:65], v[160:163], v[192:195], v[62:65]
	v_mfma_f32_16x16x32_bf16 v[58:61], v[168:171], v[192:195], v[58:61]
	v_mfma_f32_16x16x32_bf16 v[46:49], v[160:163], v[200:203], v[46:49]
	v_mfma_f32_16x16x32_bf16 v[42:45], v[168:171], v[200:203], v[42:45]
	v_mfma_f32_16x16x32_bf16 v[30:33], v[160:163], v[208:211], v[30:33]
	v_mfma_f32_16x16x32_bf16 v[26:29], v[168:171], v[208:211], v[26:29]
	v_mfma_f32_16x16x32_bf16 v[14:17], v[160:163], v[216:219], v[14:17]
	v_mfma_f32_16x16x32_bf16 v[10:13], v[168:171], v[216:219], v[10:13]
	s_setprio 0
	s_setprio 1
	v_mfma_f32_16x16x32_bf16 v[54:57], v[172:175], v[188:191], v[54:57]
	v_mfma_f32_16x16x32_bf16 v[50:53], v[180:183], v[188:191], v[50:53]
	v_mfma_f32_16x16x32_bf16 v[38:41], v[172:175], v[196:199], v[38:41]
	v_mfma_f32_16x16x32_bf16 v[34:37], v[180:183], v[196:199], v[34:37]
	v_mfma_f32_16x16x32_bf16 v[22:25], v[172:175], v[204:207], v[22:25]
	v_mfma_f32_16x16x32_bf16 v[18:21], v[180:183], v[204:207], v[18:21]
	v_mfma_f32_16x16x32_bf16 v[6:9], v[172:175], v[212:215], v[6:9]
	v_mfma_f32_16x16x32_bf16 v[2:5], v[180:183], v[212:215], v[2:5]
	v_mfma_f32_16x16x32_bf16 v[54:57], v[176:179], v[192:195], v[54:57]
	v_mfma_f32_16x16x32_bf16 v[50:53], v[184:187], v[192:195], v[50:53]
	v_mfma_f32_16x16x32_bf16 v[38:41], v[176:179], v[200:203], v[38:41]
	v_mfma_f32_16x16x32_bf16 v[34:37], v[184:187], v[200:203], v[34:37]
	v_mfma_f32_16x16x32_bf16 v[22:25], v[176:179], v[208:211], v[22:25]
	v_mfma_f32_16x16x32_bf16 v[18:21], v[184:187], v[208:211], v[18:21]
	v_mfma_f32_16x16x32_bf16 v[6:9], v[176:179], v[216:219], v[6:9]
	v_mfma_f32_16x16x32_bf16 v[2:5], v[184:187], v[216:219], v[2:5]
	s_setprio 0
	s_barrier
	s_add_i32 s70, 0, 0x18000
	v_add_u32_e32 v146, s70, v149
	s_add_i32 s71, 0, 0x1c000
	ds_read_b128 v[156:159], v146
	ds_read_b128 v[160:163], v146 offset:1024
	ds_read_b128 v[164:167], v146 offset:2048
	ds_read_b128 v[168:171], v146 offset:3072
	v_add_u32_e32 v146, s71, v149
	ds_read_b128 v[172:175], v146
	ds_read_b128 v[176:179], v146 offset:1024
	ds_read_b128 v[180:183], v146 offset:2048
	ds_read_b128 v[184:187], v146 offset:3072
	s_add_u32 s8, s8, 0x40000
	s_addc_u32 s9, s9, 0
	s_mov_b32 m0, s48
	v_lshl_add_u64 v[226:227], s[8:9], 0, v[130:131]
	ds_read_b128 v[188:191], v155 offset:32768
	ds_read_b128 v[192:195], v155 offset:33792
	ds_read_b128 v[196:199], v155 offset:34816
	ds_read_b128 v[200:203], v155 offset:35840
	ds_read_b128 v[204:207], v155 offset:36864
	ds_read_b128 v[208:211], v155 offset:37888
	ds_read_b128 v[212:215], v155 offset:38912
	ds_read_b128 v[216:219], v155 offset:39936
	global_load_lds_dwordx4 v[226:227], off
	v_lshl_add_u64 v[226:227], s[8:9], 0, v[134:135]
	s_mov_b32 m0, s49
	s_nop 0
	global_load_lds_dwordx4 v[226:227], off
	s_waitcnt vmcnt(8)
	s_waitcnt lgkmcnt(0)
	s_barrier
	s_setprio 1
	s_waitcnt lgkmcnt(0)
	s_nop 0
	v_mfma_f32_16x16x32_bf16 v[126:129], v[156:159], v[188:191], v[126:129]
	v_mfma_f32_16x16x32_bf16 v[122:125], v[164:167], v[188:191], v[122:125]
	v_mfma_f32_16x16x32_bf16 v[110:113], v[156:159], v[196:199], v[110:113]
	v_mfma_f32_16x16x32_bf16 v[106:109], v[164:167], v[196:199], v[106:109]
	v_mfma_f32_16x16x32_bf16 v[94:97], v[156:159], v[204:207], v[94:97]
	v_mfma_f32_16x16x32_bf16 v[90:93], v[164:167], v[204:207], v[90:93]
	v_mfma_f32_16x16x32_bf16 v[78:81], v[156:159], v[212:215], v[78:81]
	v_mfma_f32_16x16x32_bf16 v[74:77], v[164:167], v[212:215], v[74:77]
	v_mfma_f32_16x16x32_bf16 v[126:129], v[160:163], v[192:195], v[126:129]
	v_mfma_f32_16x16x32_bf16 v[122:125], v[168:171], v[192:195], v[122:125]
	v_mfma_f32_16x16x32_bf16 v[110:113], v[160:163], v[200:203], v[110:113]
	v_mfma_f32_16x16x32_bf16 v[106:109], v[168:171], v[200:203], v[106:109]
	v_mfma_f32_16x16x32_bf16 v[94:97], v[160:163], v[208:211], v[94:97]
	v_mfma_f32_16x16x32_bf16 v[90:93], v[168:171], v[208:211], v[90:93]
	v_mfma_f32_16x16x32_bf16 v[78:81], v[160:163], v[216:219], v[78:81]
	v_mfma_f32_16x16x32_bf16 v[74:77], v[168:171], v[216:219], v[74:77]
	s_setprio 0
	s_setprio 1
	v_mfma_f32_16x16x32_bf16 v[118:121], v[172:175], v[188:191], v[118:121]
	v_mfma_f32_16x16x32_bf16 v[114:117], v[180:183], v[188:191], v[114:117]
	v_mfma_f32_16x16x32_bf16 v[102:105], v[172:175], v[196:199], v[102:105]
	v_mfma_f32_16x16x32_bf16 v[98:101], v[180:183], v[196:199], v[98:101]
	v_mfma_f32_16x16x32_bf16 v[86:89], v[172:175], v[204:207], v[86:89]
	v_mfma_f32_16x16x32_bf16 v[82:85], v[180:183], v[204:207], v[82:85]
	v_mfma_f32_16x16x32_bf16 v[70:73], v[172:175], v[212:215], v[70:73]
	v_mfma_f32_16x16x32_bf16 v[66:69], v[180:183], v[212:215], v[66:69]
	v_mfma_f32_16x16x32_bf16 v[118:121], v[176:179], v[192:195], v[118:121]
	v_mfma_f32_16x16x32_bf16 v[114:117], v[184:187], v[192:195], v[114:117]
	v_mfma_f32_16x16x32_bf16 v[102:105], v[176:179], v[200:203], v[102:105]
	v_mfma_f32_16x16x32_bf16 v[98:101], v[184:187], v[200:203], v[98:101]
	v_mfma_f32_16x16x32_bf16 v[86:89], v[176:179], v[208:211], v[86:89]
	v_mfma_f32_16x16x32_bf16 v[82:85], v[184:187], v[208:211], v[82:85]
	v_mfma_f32_16x16x32_bf16 v[70:73], v[176:179], v[216:219], v[70:73]
	v_mfma_f32_16x16x32_bf16 v[66:69], v[184:187], v[216:219], v[66:69]
	s_setprio 0
	s_barrier
	s_cmp_lg_u32 s12, s0
	s_cbranch_scc1 .Lmy_p8_nostat
	v_add_f32_e32 v236, v228, v229
	v_add_f32_e32 v240, v230, v231
	v_add_f32_e32 v237, v232, v233
	v_add_f32_e32 v241, v234, v235
	v_add_f32_e32 v236, v236, v240
	v_add_f32_e32 v237, v237, v241
	v_mov_b32_e32 v240, 0x20800
	v_lshl_add_u32 v240, v0, 3, v240
	ds_write_b64 v240, v[236:237]
.Lmy_p8_nostat:
	s_add_i32 s8, s70, s45
	v_lshl_add_u64 v[138:139], v[138:139], 0, s[20:21]
	s_mov_b32 m0, s8
	ds_read_b128 v[188:191], v155 offset:49152
	ds_read_b128 v[192:195], v155 offset:50176
	ds_read_b128 v[196:199], v155 offset:51200
	ds_read_b128 v[200:203], v155 offset:52224
	ds_read_b128 v[204:207], v155 offset:53248
	ds_read_b128 v[208:211], v155 offset:54272
	ds_read_b128 v[212:215], v155 offset:55296
	ds_read_b128 v[216:219], v155 offset:56320
	global_load_lds_dwordx4 v[138:139], off
	s_add_i32 m0, s8, 0x2000
	s_add_u32 s6, s6, 0x10080
	v_lshl_add_u64 v[138:139], v[220:221], 0, s[20:21]
	s_addc_u32 s7, s7, 0
	s_add_i32 s8, s71, s45
	global_load_lds_dwordx4 v[138:139], off
	v_lshl_add_u64 v[138:139], s[6:7], 0, v[132:133]
	s_mov_b32 m0, s8
	s_nop 0
	global_load_lds_dwordx4 v[138:139], off
	v_lshl_add_u64 v[138:139], s[6:7], 0, v[136:137]
	s_add_i32 m0, s8, 0x2000
	s_nop 0
	global_load_lds_dwordx4 v[138:139], off
	v_lshl_add_u64 v[138:139], v[222:223], 0, s[20:21]
	s_mov_b32 m0, s53
	s_nop 0
	global_load_lds_dwordx4 v[138:139], off
	v_lshl_add_u64 v[138:139], v[224:225], 0, s[20:21]
	s_mov_b32 m0, s54
	s_nop 0
	global_load_lds_dwordx4 v[138:139], off
	s_waitcnt vmcnt(8)
	s_waitcnt lgkmcnt(0)
	s_barrier
	s_setprio 1
	s_waitcnt lgkmcnt(0)
	v_mfma_f32_16x16x32_bf16 v[62:65], v[156:159], v[188:191], v[62:65]
	v_mfma_f32_16x16x32_bf16 v[58:61], v[164:167], v[188:191], v[58:61]
	v_mfma_f32_16x16x32_bf16 v[46:49], v[156:159], v[196:199], v[46:49]
	v_mfma_f32_16x16x32_bf16 v[42:45], v[164:167], v[196:199], v[42:45]
	v_mfma_f32_16x16x32_bf16 v[30:33], v[156:159], v[204:207], v[30:33]
	v_mfma_f32_16x16x32_bf16 v[26:29], v[164:167], v[204:207], v[26:29]
	v_mfma_f32_16x16x32_bf16 v[14:17], v[156:159], v[212:215], v[14:17]
	v_mfma_f32_16x16x32_bf16 v[10:13], v[164:167], v[212:215], v[10:13]
	v_mfma_f32_16x16x32_bf16 v[62:65], v[160:163], v[192:195], v[62:65]
	v_mfma_f32_16x16x32_bf16 v[58:61], v[168:171], v[192:195], v[58:61]
	v_mfma_f32_16x16x32_bf16 v[46:49], v[160:163], v[200:203], v[46:49]
	v_mfma_f32_16x16x32_bf16 v[42:45], v[168:171], v[200:203], v[42:45]
	v_mfma_f32_16x16x32_bf16 v[30:33], v[160:163], v[208:211], v[30:33]
	v_mfma_f32_16x16x32_bf16 v[26:29], v[168:171], v[208:211], v[26:29]
	v_mfma_f32_16x16x32_bf16 v[14:17], v[160:163], v[216:219], v[14:17]
	v_mfma_f32_16x16x32_bf16 v[10:13], v[168:171], v[216:219], v[10:13]
	s_setprio 0
	s_setprio 1
	v_mfma_f32_16x16x32_bf16 v[54:57], v[172:175], v[188:191], v[54:57]
	v_mfma_f32_16x16x32_bf16 v[50:53], v[180:183], v[188:191], v[50:53]
	v_mfma_f32_16x16x32_bf16 v[38:41], v[172:175], v[196:199], v[38:41]
	v_mfma_f32_16x16x32_bf16 v[34:37], v[180:183], v[196:199], v[34:37]
	v_mfma_f32_16x16x32_bf16 v[22:25], v[172:175], v[204:207], v[22:25]
	v_mfma_f32_16x16x32_bf16 v[18:21], v[180:183], v[204:207], v[18:21]
	v_mfma_f32_16x16x32_bf16 v[6:9], v[172:175], v[212:215], v[6:9]
	v_mfma_f32_16x16x32_bf16 v[2:5], v[180:183], v[212:215], v[2:5]
	v_mfma_f32_16x16x32_bf16 v[54:57], v[176:179], v[192:195], v[54:57]
	v_mfma_f32_16x16x32_bf16 v[50:53], v[184:187], v[192:195], v[50:53]
	v_mfma_f32_16x16x32_bf16 v[38:41], v[176:179], v[200:203], v[38:41]
	v_mfma_f32_16x16x32_bf16 v[34:37], v[184:187], v[200:203], v[34:37]
	v_mfma_f32_16x16x32_bf16 v[22:25], v[176:179], v[208:211], v[22:25]
	v_mfma_f32_16x16x32_bf16 v[18:21], v[184:187], v[208:211], v[18:21]
	v_mfma_f32_16x16x32_bf16 v[6:9], v[176:179], v[216:219], v[6:9]
	v_mfma_f32_16x16x32_bf16 v[2:5], v[184:187], v[216:219], v[2:5]
	s_setprio 0
	s_barrier
	s_nop 0
	s_add_i32 s63, s63, 2
	s_add_u32 s64, s64, 0x100
	s_addc_u32 s65, s65, 0
	s_add_u32 s66, s66, 0x100
	s_addc_u32 s67, s67, 0
	s_add_u32 s0, s0, 0xffffff00
	s_addc_u32 s1, s1, -1
	v_lshl_add_u64 v[142:143], v[142:143], 0, s[24:25]
	s_cmp_gt_u32 s63, 13
	v_lshl_add_u64 v[144:145], v[144:145], 0, s[24:25]
	s_cbranch_scc0 .LBB0_971
	s_add_u32 s0, s61, 0x40080
	s_addc_u32 s1, s37, 0
	s_mov_b32 m0, s69
	v_lshl_add_u64 v[138:139], s[0:1], 0, v[130:131]
	global_load_lds_dwordx4 v[138:139], off
	v_lshl_add_u64 v[138:139], s[0:1], 0, v[134:135]
	s_mov_b32 m0, s68
	s_and_b64 vcc, exec, s[22:23]
	global_load_lds_dwordx4 v[138:139], off
	s_cbranch_vccz .LBB0_974
	s_barrier

.LBB0_1051:
	ds_read_b128 v[128:131], v213
	ds_read_b128 v[132:135], v213 offset:1024
	ds_read_b128 v[136:139], v213 offset:2048
	ds_read_b128 v[140:143], v213 offset:3072
	ds_read_b128 v[144:147], v214
	ds_read_b128 v[148:151], v214 offset:1024
	ds_read_b128 v[152:155], v214 offset:2048
	ds_read_b128 v[156:159], v214 offset:3072
	s_add_u32 s6, s2, 0xfff00080
	s_addc_u32 s7, s3, -1
	s_cmp_eq_u32 s58, 60
	s_cselect_b32 s55, s5, s7
	s_cselect_b32 s54, s47, s6
	s_cselect_b32 s7, s45, s57
	s_cselect_b32 s6, s53, s56
	v_lshl_add_u64 v[208:209], s[2:3], 0, v[194:195]
	s_add_i32 m0, s65, 0xc000
	ds_read_b128 v[160:163], v215
	ds_read_b128 v[164:167], v215 offset:1024
	ds_read_b128 v[168:171], v215 offset:2048
	ds_read_b128 v[172:175], v215 offset:3072
	ds_read_b128 v[176:179], v215 offset:4096
	ds_read_b128 v[180:183], v215 offset:5120
	ds_read_b128 v[204:207], v215 offset:6144
	ds_read_b128 v[220:223], v215 offset:7168
	global_load_lds_dwordx4 v[208:209], off
	v_lshl_add_u64 v[208:209], s[2:3], 0, v[196:197]
	s_add_i32 m0, s65, 0xe000
	s_nop 0
	global_load_lds_dwordx4 v[208:209], off
	s_waitcnt vmcnt(8)
	s_waitcnt lgkmcnt(0)
	s_barrier
	s_setprio 1
	s_waitcnt lgkmcnt(0)
	v_mfma_f32_16x16x32_bf16 v[124:127], v[128:131], v[160:163], v[124:127]
	v_mfma_f32_16x16x32_bf16 v[120:123], v[136:139], v[160:163], v[120:123]
	v_mfma_f32_16x16x32_bf16 v[108:111], v[128:131], v[168:171], v[108:111]
	v_mfma_f32_16x16x32_bf16 v[104:107], v[136:139], v[168:171], v[104:107]
	v_mfma_f32_16x16x32_bf16 v[92:95], v[128:131], v[176:179], v[92:95]
	v_mfma_f32_16x16x32_bf16 v[88:91], v[136:139], v[176:179], v[88:91]
	v_mfma_f32_16x16x32_bf16 v[76:79], v[128:131], v[204:207], v[76:79]
	v_mfma_f32_16x16x32_bf16 v[72:75], v[136:139], v[204:207], v[72:75]
	v_mfma_f32_16x16x32_bf16 v[124:127], v[132:135], v[164:167], v[124:127]
	v_mfma_f32_16x16x32_bf16 v[120:123], v[140:143], v[164:167], v[120:123]
	v_mfma_f32_16x16x32_bf16 v[108:111], v[132:135], v[172:175], v[108:111]
	v_mfma_f32_16x16x32_bf16 v[104:107], v[140:143], v[172:175], v[104:107]
	v_mfma_f32_16x16x32_bf16 v[92:95], v[132:135], v[180:183], v[92:95]
	v_mfma_f32_16x16x32_bf16 v[88:91], v[140:143], v[180:183], v[88:91]
	v_mfma_f32_16x16x32_bf16 v[76:79], v[132:135], v[220:223], v[76:79]
	v_mfma_f32_16x16x32_bf16 v[72:75], v[140:143], v[220:223], v[72:75]
	s_setprio 0
	s_setprio 1
	v_mfma_f32_16x16x32_bf16 v[116:119], v[144:147], v[160:163], v[116:119]
	v_mfma_f32_16x16x32_bf16 v[112:115], v[152:155], v[160:163], v[112:115]
	v_mfma_f32_16x16x32_bf16 v[100:103], v[144:147], v[168:171], v[100:103]
	v_mfma_f32_16x16x32_bf16 v[96:99], v[152:155], v[168:171], v[96:99]
	v_mfma_f32_16x16x32_bf16 v[84:87], v[144:147], v[176:179], v[84:87]
	v_mfma_f32_16x16x32_bf16 v[80:83], v[152:155], v[176:179], v[80:83]
	v_mfma_f32_16x16x32_bf16 v[68:71], v[144:147], v[204:207], v[68:71]
	v_mfma_f32_16x16x32_bf16 v[64:67], v[152:155], v[204:207], v[64:67]
	v_mfma_f32_16x16x32_bf16 v[116:119], v[148:151], v[164:167], v[116:119]
	v_mfma_f32_16x16x32_bf16 v[112:115], v[156:159], v[164:167], v[112:115]
	v_mfma_f32_16x16x32_bf16 v[100:103], v[148:151], v[172:175], v[100:103]
	v_mfma_f32_16x16x32_bf16 v[96:99], v[156:159], v[172:175], v[96:99]
	v_mfma_f32_16x16x32_bf16 v[84:87], v[148:151], v[180:183], v[84:87]
	v_mfma_f32_16x16x32_bf16 v[80:83], v[156:159], v[180:183], v[80:83]
	v_mfma_f32_16x16x32_bf16 v[68:71], v[148:151], v[220:223], v[68:71]
	v_mfma_f32_16x16x32_bf16 v[64:67], v[156:159], v[220:223], v[64:67]
	s_setprio 0
	s_barrier
	s_add_i32 s59, s82, s64
	v_lshl_add_u64 v[208:209], s[6:7], 0, v[186:187]
	s_mov_b32 m0, s59
	ds_read_b128 v[160:163], v215 offset:16384
	ds_read_b128 v[164:167], v215 offset:17408
	ds_read_b128 v[168:171], v215 offset:18432
	ds_read_b128 v[172:175], v215 offset:19456
	ds_read_b128 v[176:179], v215 offset:20480
	ds_read_b128 v[180:183], v215 offset:21504
	ds_read_b128 v[204:207], v215 offset:22528
	ds_read_b128 v[220:223], v215 offset:23552
	global_load_lds_dwordx4 v[208:209], off
	s_add_i32 m0, s59, 0x2000
	s_add_u32 vcc_lo, s6, 0x100000
	v_lshl_add_u64 v[224:225], s[6:7], 0, v[190:191]
	s_addc_u32 vcc_hi, s7, 0
	s_add_i32 s59, s83, s64
	global_load_lds_dwordx4 v[224:225], off
	v_lshl_add_u64 v[226:227], vcc, 0, v[186:187]
	s_mov_b32 m0, s59
	v_lshl_add_u64 v[228:229], s[54:55], 0, v[188:189]
	global_load_lds_dwordx4 v[226:227], off
	v_lshl_add_u64 v[226:227], vcc, 0, v[190:191]
	s_add_i32 m0, s59, 0x2000
	s_nop 0
	global_load_lds_dwordx4 v[226:227], off
	v_lshl_add_u64 v[226:227], s[54:55], 0, v[184:185]
	s_mov_b32 m0, s65
	s_nop 0
	global_load_lds_dwordx4 v[226:227], off
	s_mov_b32 m0, s66
	s_nop 0
	global_load_lds_dwordx4 v[228:229], off
	s_waitcnt vmcnt(8)
	s_waitcnt lgkmcnt(0)
	s_barrier
	s_setprio 1
	s_waitcnt lgkmcnt(0)
	s_nop 0
	v_mfma_f32_16x16x32_bf16 v[60:63], v[128:131], v[160:163], v[60:63]
	v_mfma_f32_16x16x32_bf16 v[56:59], v[136:139], v[160:163], v[56:59]
	v_mfma_f32_16x16x32_bf16 v[44:47], v[128:131], v[168:171], v[44:47]
	v_mfma_f32_16x16x32_bf16 v[40:43], v[136:139], v[168:171], v[40:43]
	v_mfma_f32_16x16x32_bf16 v[28:31], v[128:131], v[176:179], v[28:31]
	v_mfma_f32_16x16x32_bf16 v[24:27], v[136:139], v[176:179], v[24:27]
	v_mfma_f32_16x16x32_bf16 v[12:15], v[128:131], v[204:207], v[12:15]
	v_mfma_f32_16x16x32_bf16 v[8:11], v[136:139], v[204:207], v[8:11]
	v_mfma_f32_16x16x32_bf16 v[60:63], v[132:135], v[164:167], v[60:63]
	v_mfma_f32_16x16x32_bf16 v[56:59], v[140:143], v[164:167], v[56:59]
	v_mfma_f32_16x16x32_bf16 v[44:47], v[132:135], v[172:175], v[44:47]
	v_mfma_f32_16x16x32_bf16 v[40:43], v[140:143], v[172:175], v[40:43]
	v_mfma_f32_16x16x32_bf16 v[28:31], v[132:135], v[180:183], v[28:31]
	v_mfma_f32_16x16x32_bf16 v[24:27], v[140:143], v[180:183], v[24:27]
	v_mfma_f32_16x16x32_bf16 v[12:15], v[132:135], v[220:223], v[12:15]
	v_mfma_f32_16x16x32_bf16 v[8:11], v[140:143], v[220:223], v[8:11]
	s_setprio 0
	s_setprio 1
	v_mfma_f32_16x16x32_bf16 v[52:55], v[144:147], v[160:163], v[52:55]
	v_mfma_f32_16x16x32_bf16 v[48:51], v[152:155], v[160:163], v[48:51]
	v_mfma_f32_16x16x32_bf16 v[36:39], v[144:147], v[168:171], v[36:39]
	v_mfma_f32_16x16x32_bf16 v[32:35], v[152:155], v[168:171], v[32:35]
	v_mfma_f32_16x16x32_bf16 v[20:23], v[144:147], v[176:179], v[20:23]
	v_mfma_f32_16x16x32_bf16 v[16:19], v[152:155], v[176:179], v[16:19]
	v_mfma_f32_16x16x32_bf16 v[4:7], v[144:147], v[204:207], v[4:7]
	v_mfma_f32_16x16x32_bf16 v[0:3], v[152:155], v[204:207], v[0:3]
	v_mfma_f32_16x16x32_bf16 v[52:55], v[148:151], v[164:167], v[52:55]
	v_mfma_f32_16x16x32_bf16 v[48:51], v[156:159], v[164:167], v[48:51]
	v_mfma_f32_16x16x32_bf16 v[36:39], v[148:151], v[172:175], v[36:39]
	v_mfma_f32_16x16x32_bf16 v[32:35], v[156:159], v[172:175], v[32:35]
	v_mfma_f32_16x16x32_bf16 v[20:23], v[148:151], v[180:183], v[20:23]
	v_mfma_f32_16x16x32_bf16 v[16:19], v[156:159], v[180:183], v[16:19]
	v_mfma_f32_16x16x32_bf16 v[4:7], v[148:151], v[220:223], v[4:7]
	v_mfma_f32_16x16x32_bf16 v[0:3], v[156:159], v[220:223], v[0:3]
	s_setprio 0
	s_barrier
	s_add_i32 s59, 0, 0x18000
	s_add_i32 vcc_lo, 0, 0x1c000
	v_add_u32_e32 v140, s59, v212
	v_add_u32_e32 v156, vcc_lo, v212
	ds_read_b128 v[128:131], v140
	ds_read_b128 v[132:135], v140 offset:1024
	ds_read_b128 v[136:139], v140 offset:2048
	ds_read_b128 v[140:143], v140 offset:3072
	ds_read_b128 v[144:147], v156
	ds_read_b128 v[148:151], v156 offset:1024
	ds_read_b128 v[152:155], v156 offset:2048
	ds_read_b128 v[156:159], v156 offset:3072
	s_add_u32 s54, s54, 0x100000
	s_addc_u32 s55, s55, 0
	s_mov_b32 m0, s67
	v_lshl_add_u64 v[230:231], s[54:55], 0, v[184:185]
	ds_read_b128 v[160:163], v215 offset:32768
	ds_read_b128 v[164:167], v215 offset:33792
	ds_read_b128 v[168:171], v215 offset:34816
	ds_read_b128 v[172:175], v215 offset:35840
	ds_read_b128 v[176:179], v215 offset:36864
	ds_read_b128 v[180:183], v215 offset:37888
	ds_read_b128 v[204:207], v215 offset:38912
	ds_read_b128 v[220:223], v215 offset:39936
	global_load_lds_dwordx4 v[230:231], off
	v_lshl_add_u64 v[230:231], s[54:55], 0, v[188:189]
	s_mov_b32 m0, s68
	s_nop 0
	global_load_lds_dwordx4 v[230:231], off
	s_waitcnt vmcnt(8)
	s_waitcnt lgkmcnt(0)
	s_barrier
	s_setprio 1
	s_waitcnt lgkmcnt(0)
	s_nop 0
	v_mfma_f32_16x16x32_bf16 v[124:127], v[128:131], v[160:163], v[124:127]
	v_mfma_f32_16x16x32_bf16 v[120:123], v[136:139], v[160:163], v[120:123]
	v_mfma_f32_16x16x32_bf16 v[108:111], v[128:131], v[168:171], v[108:111]
	v_mfma_f32_16x16x32_bf16 v[104:107], v[136:139], v[168:171], v[104:107]
	v_mfma_f32_16x16x32_bf16 v[92:95], v[128:131], v[176:179], v[92:95]
	v_mfma_f32_16x16x32_bf16 v[88:91], v[136:139], v[176:179], v[88:91]
	v_mfma_f32_16x16x32_bf16 v[76:79], v[128:131], v[204:207], v[76:79]
	v_mfma_f32_16x16x32_bf16 v[72:75], v[136:139], v[204:207], v[72:75]
	v_mfma_f32_16x16x32_bf16 v[124:127], v[132:135], v[164:167], v[124:127]
	v_mfma_f32_16x16x32_bf16 v[120:123], v[140:143], v[164:167], v[120:123]
	v_mfma_f32_16x16x32_bf16 v[108:111], v[132:135], v[172:175], v[108:111]
	v_mfma_f32_16x16x32_bf16 v[104:107], v[140:143], v[172:175], v[104:107]
	v_mfma_f32_16x16x32_bf16 v[92:95], v[132:135], v[180:183], v[92:95]
	v_mfma_f32_16x16x32_bf16 v[88:91], v[140:143], v[180:183], v[88:91]
	v_mfma_f32_16x16x32_bf16 v[76:79], v[132:135], v[220:223], v[76:79]
	v_mfma_f32_16x16x32_bf16 v[72:75], v[140:143], v[220:223], v[72:75]
	s_setprio 0
	s_setprio 1
	v_mfma_f32_16x16x32_bf16 v[116:119], v[144:147], v[160:163], v[116:119]
	v_mfma_f32_16x16x32_bf16 v[112:115], v[152:155], v[160:163], v[112:115]
	v_mfma_f32_16x16x32_bf16 v[100:103], v[144:147], v[168:171], v[100:103]
	v_mfma_f32_16x16x32_bf16 v[96:99], v[152:155], v[168:171], v[96:99]
	v_mfma_f32_16x16x32_bf16 v[84:87], v[144:147], v[176:179], v[84:87]
	v_mfma_f32_16x16x32_bf16 v[80:83], v[152:155], v[176:179], v[80:83]
	v_mfma_f32_16x16x32_bf16 v[68:71], v[144:147], v[204:207], v[68:71]
	v_mfma_f32_16x16x32_bf16 v[64:67], v[152:155], v[204:207], v[64:67]
	v_mfma_f32_16x16x32_bf16 v[116:119], v[148:151], v[164:167], v[116:119]
	v_mfma_f32_16x16x32_bf16 v[112:115], v[156:159], v[164:167], v[112:115]
	v_mfma_f32_16x16x32_bf16 v[100:103], v[148:151], v[172:175], v[100:103]
	v_mfma_f32_16x16x32_bf16 v[96:99], v[156:159], v[172:175], v[96:99]
	v_mfma_f32_16x16x32_bf16 v[84:87], v[148:151], v[180:183], v[84:87]
	v_mfma_f32_16x16x32_bf16 v[80:83], v[156:159], v[180:183], v[80:83]
	v_mfma_f32_16x16x32_bf16 v[68:71], v[148:151], v[220:223], v[68:71]
	v_mfma_f32_16x16x32_bf16 v[64:67], v[156:159], v[220:223], v[64:67]
	s_setprio 0
	s_barrier
	s_add_i32 s54, s59, s64
	v_lshl_add_u64 v[208:209], v[208:209], 0, s[18:19]
	s_mov_b32 m0, s54
	ds_read_b128 v[160:163], v215 offset:49152
	ds_read_b128 v[164:167], v215 offset:50176
	ds_read_b128 v[168:171], v215 offset:51200
	ds_read_b128 v[172:175], v215 offset:52224
	ds_read_b128 v[176:179], v215 offset:53248
	ds_read_b128 v[180:183], v215 offset:54272
	ds_read_b128 v[204:207], v215 offset:55296
	ds_read_b128 v[220:223], v215 offset:56320
	global_load_lds_dwordx4 v[208:209], off
	s_add_i32 m0, s54, 0x2000
	s_add_u32 s6, s6, 0x100080
	v_lshl_add_u64 v[208:209], v[224:225], 0, s[18:19]
	s_addc_u32 s7, s7, 0
	s_add_i32 s54, vcc_lo, s64
	global_load_lds_dwordx4 v[208:209], off
	v_lshl_add_u64 v[208:209], s[6:7], 0, v[186:187]
	s_mov_b32 m0, s54
	s_nop 0
	global_load_lds_dwordx4 v[208:209], off
	v_lshl_add_u64 v[208:209], s[6:7], 0, v[190:191]
	s_add_i32 m0, s54, 0x2000
	s_nop 0
	global_load_lds_dwordx4 v[208:209], off
	v_lshl_add_u64 v[208:209], v[226:227], 0, s[18:19]
	s_mov_b32 m0, s74
	s_nop 0
	global_load_lds_dwordx4 v[208:209], off
	v_lshl_add_u64 v[208:209], v[228:229], 0, s[18:19]
	s_mov_b32 m0, s75
	s_nop 0
	global_load_lds_dwordx4 v[208:209], off
	s_waitcnt vmcnt(8)
	s_waitcnt lgkmcnt(0)
	s_barrier
	s_setprio 1
	s_waitcnt lgkmcnt(0)
	v_mfma_f32_16x16x32_bf16 v[60:63], v[128:131], v[160:163], v[60:63]
	v_mfma_f32_16x16x32_bf16 v[56:59], v[136:139], v[160:163], v[56:59]
	v_mfma_f32_16x16x32_bf16 v[44:47], v[128:131], v[168:171], v[44:47]
	v_mfma_f32_16x16x32_bf16 v[40:43], v[136:139], v[168:171], v[40:43]
	v_mfma_f32_16x16x32_bf16 v[28:31], v[128:131], v[176:179], v[28:31]
	v_mfma_f32_16x16x32_bf16 v[24:27], v[136:139], v[176:179], v[24:27]
	v_mfma_f32_16x16x32_bf16 v[12:15], v[128:131], v[204:207], v[12:15]
	v_mfma_f32_16x16x32_bf16 v[8:11], v[136:139], v[204:207], v[8:11]
	v_mfma_f32_16x16x32_bf16 v[60:63], v[132:135], v[164:167], v[60:63]
	v_mfma_f32_16x16x32_bf16 v[56:59], v[140:143], v[164:167], v[56:59]
	v_mfma_f32_16x16x32_bf16 v[44:47], v[132:135], v[172:175], v[44:47]
	v_mfma_f32_16x16x32_bf16 v[40:43], v[140:143], v[172:175], v[40:43]
	v_mfma_f32_16x16x32_bf16 v[28:31], v[132:135], v[180:183], v[28:31]
	v_mfma_f32_16x16x32_bf16 v[24:27], v[140:143], v[180:183], v[24:27]
	v_mfma_f32_16x16x32_bf16 v[12:15], v[132:135], v[220:223], v[12:15]
	v_mfma_f32_16x16x32_bf16 v[8:11], v[140:143], v[220:223], v[8:11]
	s_setprio 0
	s_setprio 1
	v_mfma_f32_16x16x32_bf16 v[52:55], v[144:147], v[160:163], v[52:55]
	v_mfma_f32_16x16x32_bf16 v[48:51], v[152:155], v[160:163], v[48:51]
	v_mfma_f32_16x16x32_bf16 v[36:39], v[144:147], v[168:171], v[36:39]
	v_mfma_f32_16x16x32_bf16 v[32:35], v[152:155], v[168:171], v[32:35]
	v_mfma_f32_16x16x32_bf16 v[20:23], v[144:147], v[176:179], v[20:23]
	v_mfma_f32_16x16x32_bf16 v[16:19], v[152:155], v[176:179], v[16:19]
	v_mfma_f32_16x16x32_bf16 v[4:7], v[144:147], v[204:207], v[4:7]
	v_mfma_f32_16x16x32_bf16 v[0:3], v[152:155], v[204:207], v[0:3]
	v_mfma_f32_16x16x32_bf16 v[52:55], v[148:151], v[164:167], v[52:55]
	v_mfma_f32_16x16x32_bf16 v[48:51], v[156:159], v[164:167], v[48:51]
	v_mfma_f32_16x16x32_bf16 v[36:39], v[148:151], v[172:175], v[36:39]
	v_mfma_f32_16x16x32_bf16 v[32:35], v[156:159], v[172:175], v[32:35]
	v_mfma_f32_16x16x32_bf16 v[20:23], v[148:151], v[180:183], v[20:23]
	v_mfma_f32_16x16x32_bf16 v[16:19], v[156:159], v[180:183], v[16:19]
	v_mfma_f32_16x16x32_bf16 v[4:7], v[148:151], v[220:223], v[4:7]
	v_mfma_f32_16x16x32_bf16 v[0:3], v[156:159], v[220:223], v[0:3]
	s_setprio 0
	s_barrier
	s_add_i32 s58, s58, 2
	s_add_u32 s2, s2, 0x100
	s_addc_u32 s3, s3, 0
	s_add_u32 s56, s56, 0x100
	s_addc_u32 s57, s57, 0
	s_cmp_gt_u32 s58, 61
	s_cbranch_scc0 .LBB0_1051
	s_and_b64 vcc, exec, s[20:21]
	s_cbranch_vccz .LBB0_1054
	s_barrier
